# inproj1 q/k epilogue, first tile of each pair too: rope cos/sin fetched by a rolling two-group-deep prefetch into 16 registers spilled to private LDS cells (no extra barrier); second tile keeps the on
# baseline (speedup 1.0000x reference)
.LBB0_437:
	s_andn2_b64 vcc, exec, s[4:5]
	s_mov_b64 s[4:5], 0x1000
	s_cbranch_vccnz .LBB0_443
	s_cmp_lg_u32 s65, 0
	s_cbranch_scc0 .LBB0_447
	s_lshl_b64 s[58:59], s[0:1], 13
	s_cmp_eq_u32 s65, 1
	s_cselect_b64 s[56:57], -1, 0
	s_and_b64 s[0:1], s[56:57], exec
	s_cselect_b32 s1, s43, s45
	s_cselect_b32 s0, s42, s44
	v_mov_b32_e32 v120, v18
	v_mov_b32_e32 v121, v22
	v_mul_f32_e32 v122, v120, v120
	v_mul_f32_e32 v123, v121, v121
	global_load_dword v143, v192, s[0:1]
	global_load_dword v141, v192, s[0:1] offset:64
	global_load_dword v125, v192, s[0:1] offset:128
	global_load_dword v121, v192, s[0:1] offset:192
	global_load_dword v142, v192, s[0:1] offset:256
	global_load_dword v140, v192, s[0:1] offset:320
	v_and_b32_e32 v77, 64, v201
	v_xor_b32_e32 v76, 1, v201
	v_add_u32_e32 v77, 64, v77
	v_cmp_lt_i32_e32 vcc, v76, v77
	v_mov_b32_e32 v82, v41
	v_mov_b32_e32 v83, v45
	v_cndmask_b32_e32 v76, v201, v76, vcc
	v_lshlrev_b32_e32 v146, 2, v76
	v_xor_b32_e32 v76, 2, v201
	v_cmp_lt_i32_e32 vcc, v76, v77
	v_mul_f32_e32 v82, v82, v82
	v_mul_f32_e32 v83, v83, v83
	v_mul_f32_e32 v86, v36, v36
	v_mul_f32_e32 v87, v37, v37
	v_cndmask_b32_e32 v76, v201, v76, vcc
	v_lshlrev_b32_e32 v147, 2, v76
	v_xor_b32_e32 v76, 4, v201
	v_cmp_lt_i32_e32 vcc, v76, v77
	v_mov_b32_e32 v78, v48
	v_mov_b32_e32 v79, v52
	v_cndmask_b32_e32 v76, v201, v76, vcc
	v_lshlrev_b32_e32 v148, 2, v76
	v_xor_b32_e32 v76, 8, v201
	v_cmp_lt_i32_e32 vcc, v76, v77
	v_mov_b32_e32 v77, v44
	v_fma_f32 v86, v32, v32, v86
	v_fma_f32 v87, v33, v33, v87
	v_cndmask_b32_e32 v76, v201, v76, vcc
	v_lshlrev_b32_e32 v149, 2, v76
	v_mov_b32_e32 v76, v40
	v_mul_f32_e32 v76, v76, v76
	v_mul_f32_e32 v77, v77, v77
	v_mov_b32_e32 v88, v49
	v_mov_b32_e32 v89, v53
	v_mov_b32_e32 v126, v82
	v_mov_b32_e32 v127, v76
	v_mul_f32_e32 v78, v78, v78
	v_mul_f32_e32 v79, v79, v79
	v_mul_f32_e32 v88, v88, v88
	v_mul_f32_e32 v89, v89, v89
	v_pk_add_f32 v[86:87], v[86:87], v[126:127] op_sel:[1,0] op_sel_hi:[0,1]
	v_mov_b32_e32 v76, v83
	v_mov_b32_e32 v80, v56
	v_mov_b32_e32 v81, v60
	v_mov_b32_e32 v90, v57
	v_mov_b32_e32 v91, v61
	v_add_f32_e32 v76, v86, v76
	v_add_f32_e32 v77, v87, v77
	v_mov_b32_e32 v82, v88
	v_mov_b32_e32 v83, v78
	v_mul_f32_e32 v80, v80, v80
	v_mul_f32_e32 v81, v81, v81
	v_mul_f32_e32 v90, v90, v90
	v_mul_f32_e32 v91, v91, v91
	v_add_f32_e32 v76, v76, v82
	v_add_f32_e32 v77, v77, v83
	v_mov_b32_e32 v78, v89
	v_add_f32_e32 v76, v76, v78
	v_add_f32_e32 v77, v77, v79
	v_mov_b32_e32 v78, v90
	v_mov_b32_e32 v79, v80
	v_add_f32_e32 v76, v76, v78
	v_add_f32_e32 v77, v77, v79
	v_mov_b32_e32 v80, v91
	v_add_f32_e32 v76, v76, v80
	v_add_f32_e32 v77, v77, v81
	s_nop 1
	v_mov_b32_dpp v79, v77 quad_perm:[1,0,3,2] row_mask:0xf bank_mask:0xf
	v_mov_b32_dpp v78, v76 quad_perm:[1,0,3,2] row_mask:0xf bank_mask:0xf
	global_load_dword v124, v192, s[0:1] offset:384
	global_load_dword v120, v192, s[0:1] offset:448
	v_mov_b32_e32 v88, v3
	v_mov_b32_e32 v89, v11
	s_waitcnt lgkmcnt(0)
	v_add_f32_e32 v76, v76, v78
	v_add_f32_e32 v77, v77, v79
	s_nop 1
	v_mov_b32_dpp v79, v77 quad_perm:[2,3,0,1] row_mask:0xf bank_mask:0xf
	v_mov_b32_dpp v78, v76 quad_perm:[2,3,0,1] row_mask:0xf bank_mask:0xf
	v_mov_b32_e32 v92, v42
	v_mov_b32_e32 v93, v46
	v_mov_b32_e32 v98, v43
	v_mov_b32_e32 v99, v47
	s_waitcnt lgkmcnt(0)
	v_add_f32_e32 v76, v76, v78
	v_add_f32_e32 v77, v77, v79
	s_nop 1
	v_mov_b32_dpp v79, v77 row_half_mirror row_mask:0xf bank_mask:0xf
	v_mov_b32_dpp v78, v76 row_half_mirror row_mask:0xf bank_mask:0xf
	v_mul_f32_e32 v90, v88, v88
	v_mul_f32_e32 v91, v89, v89
	v_mov_b32_e32 v88, v27
	v_mov_b32_e32 v89, v31
	v_mul_f32_e32 v84, v38, v38
	v_mul_f32_e32 v85, v39, v39
	s_waitcnt lgkmcnt(0)
	v_add_f32_e32 v76, v76, v78
	v_add_f32_e32 v77, v77, v79
	s_nop 1
	v_mov_b32_dpp v79, v77 row_mirror row_mask:0xf bank_mask:0xf
	v_mov_b32_dpp v78, v76 row_mirror row_mask:0xf bank_mask:0xf
	v_mul_f32_e32 v92, v92, v92
	v_mul_f32_e32 v93, v93, v93
	v_mul_f32_e32 v98, v98, v98
	v_mul_f32_e32 v99, v99, v99
	v_fma_f32 v84, v34, v34, v84
	v_fma_f32 v85, v35, v35, v85
	v_mov_b32_e32 v94, v50
	s_waitcnt lgkmcnt(0)
	v_add_f32_e32 v76, v76, v78
	v_add_f32_e32 v77, v77, v79
	v_mov_b64_e32 v[78:79], s[52:53]
	v_fma_f32 v76, v76, s46, v78
	v_fma_f32 v77, v77, s46, v78
	v_mov_b32_e32 v95, v54
	v_mul_f32_e32 v126, 0x4b800000, v77
	v_cmp_gt_f32_e32 vcc, s60, v77
	v_cmp_gt_f32_e64 s[0:1], s60, v76
	v_mov_b32_e32 v100, v51
	v_cndmask_b32_e32 v77, v77, v126, vcc
	v_rsq_f32_e32 v126, v77
	v_mul_f32_e32 v77, 0x4b800000, v76
	v_cndmask_b32_e64 v76, v76, v77, s[0:1]
	v_rsq_f32_e32 v127, v76
	v_mul_f32_e32 v76, v88, v88
	v_mul_f32_e32 v77, v89, v89
	v_mul_f32_e32 v88, 0x45800000, v126
	v_mov_b32_e32 v101, v55
	v_cndmask_b32_e32 v126, v126, v88, vcc
	v_mov_b32_e32 v88, v98
	v_mov_b32_e32 v89, v92
	v_mul_f32_e32 v94, v94, v94
	v_mul_f32_e32 v95, v95, v95
	v_mul_f32_e32 v100, v100, v100
	v_mul_f32_e32 v101, v101, v101
	v_pk_add_f32 v[84:85], v[84:85], v[88:89] op_sel:[1,0] op_sel_hi:[0,1]
	v_mov_b32_e32 v92, v99
	v_mov_b32_e32 v96, v58
	v_mov_b32_e32 v97, v62
	v_mov_b32_e32 v102, v59
	v_mov_b32_e32 v103, v63
	v_add_f32_e32 v84, v84, v92
	v_add_f32_e32 v85, v85, v93
	v_mov_b32_e32 v88, v100
	v_mov_b32_e32 v89, v94
	v_mul_f32_e32 v96, v96, v96
	v_mul_f32_e32 v97, v97, v97
	v_mul_f32_e32 v102, v102, v102
	v_mul_f32_e32 v103, v103, v103
	v_add_f32_e32 v84, v84, v88
	v_add_f32_e32 v85, v85, v89
	v_mov_b32_e32 v94, v101
	v_add_f32_e32 v84, v84, v94
	v_add_f32_e32 v85, v85, v95
	v_mov_b32_e32 v88, v102
	v_mov_b32_e32 v89, v96
	v_add_f32_e32 v84, v84, v88
	v_add_f32_e32 v85, v85, v89
	v_mov_b32_e32 v96, v103
	v_add_f32_e32 v84, v84, v96
	v_add_f32_e32 v85, v85, v97
	s_nop 1
	v_mov_b32_dpp v89, v85 quad_perm:[1,0,3,2] row_mask:0xf bank_mask:0xf
	v_mov_b32_dpp v88, v84 quad_perm:[1,0,3,2] row_mask:0xf bank_mask:0xf
	v_mul_f32_e32 v144, 0x45800000, v127
	v_mov_b32_e32 v104, v16
	v_mov_b32_e32 v105, v20
	v_mov_b32_e32 v110, v17
	s_waitcnt lgkmcnt(0)
	v_add_f32_e32 v84, v84, v88
	v_add_f32_e32 v85, v85, v89
	s_nop 1
	v_mov_b32_dpp v89, v85 quad_perm:[2,3,0,1] row_mask:0xf bank_mask:0xf
	v_mov_b32_dpp v88, v84 quad_perm:[2,3,0,1] row_mask:0xf bank_mask:0xf
	v_mov_b32_e32 v111, v21
	v_cndmask_b32_e64 v96, v127, v144, s[0:1]
	v_mul_f32_e32 v104, v104, v104
	v_mul_f32_e32 v105, v105, v105
	v_mul_f32_e32 v110, v110, v110
	v_mul_f32_e32 v111, v111, v111
	v_mul_f32_e32 v114, v12, v12
	v_mul_f32_e32 v115, v13, v13
	s_waitcnt vmcnt(0)
	v_mul_f32_e32 v92, v96, v143
	v_mov_b32_e32 v106, v0
	v_mov_b32_e32 v107, v8
	v_fma_f32 v114, v4, v4, v114
	v_fma_f32 v115, v5, v5, v115
	v_mov_b32_e32 v116, v1
	v_mov_b32_e32 v117, v9
	v_mul_f32_e32 v127, v33, v92
	s_waitcnt lgkmcnt(0)
	v_add_f32_e32 v84, v84, v88
	v_add_f32_e32 v85, v85, v89
	v_mov_b32_e32 v92, v110
	v_mov_b32_e32 v93, v104
	v_mul_f32_e32 v106, v106, v106
	v_mul_f32_e32 v107, v107, v107
	v_mul_f32_e32 v116, v116, v116
	v_mul_f32_e32 v117, v117, v117
	v_mov_b32_dpp v89, v85 row_half_mirror row_mask:0xf bank_mask:0xf
	v_mov_b32_dpp v88, v84 row_half_mirror row_mask:0xf bank_mask:0xf
	v_add_f32_e32 v92, v115, v92
	v_add_f32_e32 v93, v114, v93
	v_mov_b32_e32 v104, v111
	v_mov_b32_e32 v108, v24
	v_mov_b32_e32 v109, v28
	v_mov_b32_e32 v118, v25
	v_mov_b32_e32 v119, v29
	v_add_f32_e32 v92, v92, v104
	v_add_f32_e32 v93, v93, v105
	v_mov_b32_e32 v94, v116
	v_mov_b32_e32 v95, v106
	v_mul_f32_e32 v108, v108, v108
	v_mul_f32_e32 v109, v109, v109
	v_mul_f32_e32 v118, v118, v118
	v_mul_f32_e32 v119, v119, v119
	v_add_f32_e32 v92, v92, v94
	v_add_f32_e32 v93, v93, v95
	v_mov_b32_e32 v106, v117
	v_add_f32_e32 v92, v92, v106
	v_add_f32_e32 v93, v93, v107
	v_mov_b32_e32 v94, v118
	v_mov_b32_e32 v95, v108
	v_add_f32_e32 v92, v92, v94
	v_add_f32_e32 v93, v93, v95
	v_mov_b32_e32 v108, v119
	s_waitcnt lgkmcnt(0)
	v_add_f32_e32 v84, v84, v88
	v_add_f32_e32 v85, v85, v89
	v_add_f32_e32 v92, v92, v108
	v_add_f32_e32 v93, v93, v109
	v_mov_b32_dpp v89, v85 row_mirror row_mask:0xf bank_mask:0xf
	v_mov_b32_dpp v88, v84 row_mirror row_mask:0xf bank_mask:0xf
	v_mov_b32_dpp v95, v93 quad_perm:[1,0,3,2] row_mask:0xf bank_mask:0xf
	v_mov_b32_dpp v94, v92 quad_perm:[1,0,3,2] row_mask:0xf bank_mask:0xf
	v_mul_f32_e32 v33, v96, v141
	v_mul_f32_e32 v150, v37, v33
	s_waitcnt lgkmcnt(2)
	v_add_f32_e32 v84, v84, v88
	v_add_f32_e32 v85, v85, v89
	v_mul_f32_e32 v33, v96, v125
	s_waitcnt lgkmcnt(0)
	v_add_f32_e32 v88, v92, v94
	v_add_f32_e32 v89, v93, v95
	s_nop 1
	v_mov_b32_dpp v93, v89 quad_perm:[2,3,0,1] row_mask:0xf bank_mask:0xf
	v_mov_b32_dpp v92, v88 quad_perm:[2,3,0,1] row_mask:0xf bank_mask:0xf
	v_fma_f32 v84, v84, s46, v78
	v_fma_f32 v85, v85, s46, v78
	v_mul_f32_e32 v151, v41, v33
	v_mul_f32_e32 v37, 0x4b800000, v85
	v_cmp_gt_f32_e32 vcc, s60, v85
	s_waitcnt lgkmcnt(0)
	v_add_f32_e32 v88, v88, v92
	v_add_f32_e32 v89, v89, v93
	s_nop 1
	v_mov_b32_dpp v93, v89 row_half_mirror row_mask:0xf bank_mask:0xf
	v_mov_b32_dpp v92, v88 row_half_mirror row_mask:0xf bank_mask:0xf
	v_mul_f32_e32 v41, 0x4b800000, v84
	v_cmp_gt_f32_e64 s[0:1], s60, v84
	v_cndmask_b32_e32 v37, v85, v37, vcc
	v_mul_f32_e32 v33, v96, v121
	s_waitcnt lgkmcnt(0)
	v_add_f32_e32 v88, v88, v92
	v_add_f32_e32 v89, v89, v93
	s_nop 1
	v_mov_b32_dpp v93, v89 row_mirror row_mask:0xf bank_mask:0xf
	v_mov_b32_dpp v92, v88 row_mirror row_mask:0xf bank_mask:0xf
	v_cndmask_b32_e64 v41, v84, v41, s[0:1]
	v_mul_f32_e32 v203, v45, v33
	v_mul_f32_e32 v33, v96, v142
	v_rsq_f32_e32 v37, v37
	s_waitcnt lgkmcnt(0)
	v_add_f32_e32 v84, v88, v92
	v_add_f32_e32 v85, v89, v93
	v_mul_f32_e32 v204, v49, v33
	v_fma_f32 v84, v84, s46, v78
	v_fma_f32 v85, v85, s46, v78
	v_mul_f32_e32 v33, v96, v140
	v_mul_f32_e32 v45, 0x4b800000, v85
	v_cmp_gt_f32_e64 s[4:5], s60, v85
	v_rsq_f32_e32 v41, v41
	v_mul_f32_e32 v104, v53, v33
	v_cndmask_b32_e64 v45, v85, v45, s[4:5]
	v_mul_f32_e32 v33, v96, v124
	v_rsq_f32_e32 v45, v45
	v_mul_f32_e32 v105, v57, v33
	v_mul_f32_e32 v33, v96, v120
	v_mul_f32_e32 v106, v61, v33
	v_mul_f32_e32 v33, 0x45800000, v37
	v_cndmask_b32_e32 v92, v37, v33, vcc
	v_mul_f32_e32 v33, 0x45800000, v41
	v_cndmask_b32_e64 v88, v41, v33, s[0:1]
	v_mul_f32_e32 v33, 0x45800000, v45
	v_cndmask_b32_e64 v108, v45, v33, s[4:5]
	v_mul_f32_e32 v33, 0x4b800000, v84
	v_cmp_gt_f32_e32 vcc, s60, v84
	v_mov_b32_e32 v86, v19
	v_mov_b32_e32 v87, v23
	v_cndmask_b32_e32 v33, v84, v33, vcc
	v_lshl_add_u64 v[84:85], s[58:59], 0, v[72:73]
	v_lshlrev_b64 v[144:145], 2, v[84:85]
	s_cmp_lg_u32 s89, 0
	s_cbranch_scc1 .Lmy_rp_p2
	ds_write_b32 v129, v66 offset:45056
	ds_write_b32 v129, v67 offset:45060
	ds_write_b32 v129, v68 offset:45064
	ds_write_b32 v129, v69 offset:45068
	ds_write_b32 v129, v71 offset:49152
	ds_write_b32 v129, v74 offset:49156
	ds_write_b32 v129, v75 offset:49160
	ds_write_b32 v129, v160 offset:49164
	ds_write_b32 v129, v161 offset:53248
	ds_write_b32 v129, v162 offset:53252
	ds_write_b32 v129, v185 offset:53256
	ds_write_b32 v129, v186 offset:53260
	ds_write_b32 v129, v187 offset:57344
	ds_write_b32 v129, v207 offset:57348
	ds_write_b32 v129, v212 offset:57352
	ds_write_b32 v129, v213 offset:57356
	s_waitcnt lgkmcnt(0)
	s_add_u32 s10, s6, 0x1000
	s_addc_u32 s11, s7, 0
	s_add_u32 s12, s8, 0x1000
	s_addc_u32 s13, s9, 0
	global_load_dword v161, v144, s[6:7] offset:256
	global_load_dword v162, v144, s[8:9] offset:256
	global_load_dword v185, v144, s[6:7] offset:320
	global_load_dword v186, v144, s[8:9] offset:320
	global_load_dword v187, v144, s[6:7] offset:384
	global_load_dword v207, v144, s[8:9] offset:384
	global_load_dword v212, v144, s[6:7] offset:448
	global_load_dword v213, v144, s[8:9] offset:448
	global_load_dword v66, v144, s[6:7] offset:512
	global_load_dword v67, v144, s[8:9] offset:512
	global_load_dword v68, v144, s[6:7] offset:576
	global_load_dword v69, v144, s[8:9] offset:576
	global_load_dword v71, v144, s[6:7] offset:640
	global_load_dword v74, v144, s[8:9] offset:640
	global_load_dword v75, v144, s[6:7] offset:704
	global_load_dword v160, v144, s[8:9] offset:704
	v_lshl_add_u64 v[84:85], s[6:7], 0, v[144:145]
	v_lshl_add_u64 v[94:95], s[8:9], 0, v[144:145]
	global_load_dword v85, v[84:85], off
	s_nop 0
	global_load_dword v84, v[94:95], off
	v_or_b32_e32 v94, 64, v144
	v_mov_b32_e32 v95, v145
	v_lshl_add_u64 v[96:97], s[6:7], 0, v[94:95]
	v_lshl_add_u64 v[94:95], s[8:9], 0, v[94:95]
	global_load_dword v97, v[96:97], off
	s_nop 0
	global_load_dword v96, v[94:95], off
	v_or_b32_e32 v98, 0x80, v144
	v_mov_b32_e32 v99, v145
	v_lshl_add_u64 v[100:101], s[6:7], 0, v[98:99]
	v_lshl_add_u64 v[98:99], s[8:9], 0, v[98:99]
	global_load_dword v101, v[100:101], off
	s_nop 0
	global_load_dword v100, v[98:99], off
	v_or_b32_e32 v98, 0xc0, v144
	v_mov_b32_e32 v99, v145
	v_lshl_add_u64 v[102:103], s[6:7], 0, v[98:99]
	v_lshl_add_u64 v[98:99], s[8:9], 0, v[98:99]
	global_load_dword v103, v[102:103], off
	s_nop 0
	global_load_dword v102, v[98:99], off
	v_mul_f32_e32 v112, v14, v14
	v_mul_f32_e32 v113, v15, v15
	v_mul_f32_e32 v86, v86, v86
	v_mul_f32_e32 v87, v87, v87
	v_fma_f32 v112, v6, v6, v112
	v_fma_f32 v113, v7, v7, v113
	v_mov_b32_e32 v80, v2
	v_mov_b32_e32 v81, v10
	v_mov_b32_e32 v94, v86
	v_mov_b32_e32 v95, v122
	v_mul_f32_e32 v80, v80, v80
	v_mul_f32_e32 v81, v81, v81
	v_add_f32_e32 v94, v113, v94
	v_add_f32_e32 v95, v112, v95
	v_mov_b32_e32 v122, v87
	v_mov_b32_e32 v82, v26
	v_mov_b32_e32 v83, v30
	v_add_f32_e32 v86, v94, v122
	v_add_f32_e32 v87, v95, v123
	v_mov_b32_e32 v94, v90
	v_mov_b32_e32 v95, v80
	v_mul_f32_e32 v82, v82, v82
	v_mul_f32_e32 v83, v83, v83
	v_add_f32_e32 v86, v86, v94
	v_add_f32_e32 v87, v87, v95
	v_mov_b32_e32 v80, v91
	v_add_f32_e32 v80, v86, v80
	v_add_f32_e32 v81, v87, v81
	v_mov_b32_e32 v86, v76
	v_mov_b32_e32 v87, v82
	v_add_f32_e32 v80, v80, v86
	v_add_f32_e32 v81, v81, v87
	v_mov_b32_e32 v82, v77
	v_add_f32_e32 v76, v80, v82
	v_add_f32_e32 v77, v81, v83
	s_nop 1
	v_mov_b32_dpp v81, v77 quad_perm:[1,0,3,2] row_mask:0xf bank_mask:0xf
	v_mov_b32_dpp v80, v76 quad_perm:[1,0,3,2] row_mask:0xf bank_mask:0xf
	v_rsq_f32_e32 v33, v33
	v_mov_b32_e32 v49, v32
	v_mov_b32_e32 v53, v36
	v_mov_b32_e32 v57, v40
	s_waitcnt lgkmcnt(0)
	v_add_f32_e32 v76, v76, v80
	v_add_f32_e32 v77, v77, v81
	s_nop 1
	v_mov_b32_dpp v81, v77 quad_perm:[2,3,0,1] row_mask:0xf bank_mask:0xf
	v_mov_b32_dpp v80, v76 quad_perm:[2,3,0,1] row_mask:0xf bank_mask:0xf
	v_mul_f32_e32 v37, 0x45800000, v33
	v_cndmask_b32_e32 v33, v33, v37, vcc
	v_mul_f32_e32 v37, v33, v143
	v_mul_f32_e32 v41, v5, v37
	s_waitcnt lgkmcnt(0)
	v_add_f32_e32 v76, v76, v80
	v_add_f32_e32 v77, v77, v81
	s_nop 1
	v_mov_b32_dpp v81, v77 row_half_mirror row_mask:0xf bank_mask:0xf
	v_mov_b32_dpp v80, v76 row_half_mirror row_mask:0xf bank_mask:0xf
	v_mul_f32_e32 v5, v33, v141
	v_mul_f32_e32 v45, v13, v5
	v_mul_f32_e32 v5, v33, v125
	v_mul_f32_e32 v5, v17, v5
	s_waitcnt lgkmcnt(0)
	v_add_f32_e32 v76, v76, v80
	v_add_f32_e32 v77, v77, v81
	s_nop 1
	v_mov_b32_dpp v81, v77 row_mirror row_mask:0xf bank_mask:0xf
	v_mov_b32_dpp v80, v76 row_mirror row_mask:0xf bank_mask:0xf
	v_mul_f32_e32 v13, v33, v121
	v_mul_f32_e32 v17, v33, v142
	v_mul_f32_e32 v13, v21, v13
	v_mul_f32_e32 v21, v1, v17
	v_mul_f32_e32 v1, v33, v140
	s_waitcnt lgkmcnt(0)
	v_add_f32_e32 v76, v76, v80
	v_add_f32_e32 v77, v77, v81
	v_mul_f32_e32 v109, v9, v1
	v_mul_f32_e32 v1, v33, v124
	v_fma_f32 v76, v76, s46, v78
	v_fma_f32 v77, v77, s46, v78
	v_mul_f32_e32 v17, v25, v1
	v_mul_f32_e32 v9, 0x4b800000, v77
	v_cmp_gt_f32_e32 vcc, s60, v77
	v_mul_f32_e32 v25, 0x4b800000, v76
	v_cmp_gt_f32_e64 s[0:1], s60, v76
	v_cndmask_b32_e32 v9, v77, v9, vcc
	v_mul_f32_e32 v1, v33, v120
	v_cndmask_b32_e64 v25, v76, v25, s[0:1]
	v_mul_f32_e32 v76, v126, v142
	v_mul_f32_e32 v77, v126, v143
	v_mul_f32_e32 v32, v48, v76
	v_mul_f32_e32 v33, v49, v77
	s_waitcnt vmcnt(7)
	v_mov_b32_e32 v76, v85
	s_waitcnt vmcnt(6)
	v_mov_b32_e32 v77, v84
	v_rsq_f32_e32 v9, v9
	v_mul_f32_e32 v48, v32, v84
	v_mul_f32_e32 v49, v33, v85
	v_mul_f32_e32 v32, v32, v76
	v_mul_f32_e32 v33, v33, v77
	v_mul_f32_e32 v76, v126, v140
	v_mul_f32_e32 v77, v126, v141
	v_rsq_f32_e32 v25, v25
	v_mul_f32_e32 v36, v52, v76
	v_mul_f32_e32 v37, v53, v77
	s_waitcnt vmcnt(5)
	v_mov_b32_e32 v76, v97
	s_waitcnt vmcnt(4)
	v_mov_b32_e32 v77, v96
	v_mul_f32_e32 v52, v36, v96
	v_mul_f32_e32 v53, v37, v97
	v_mul_f32_e32 v36, v36, v76
	v_mul_f32_e32 v37, v37, v77
	v_mul_f32_e32 v76, v126, v124
	v_mul_f32_e32 v77, v126, v125
	v_mul_f32_e32 v56, v56, v76
	v_mul_f32_e32 v57, v57, v77
	s_waitcnt vmcnt(3)
	v_mov_b32_e32 v78, v101
	s_waitcnt vmcnt(2)
	v_mov_b32_e32 v79, v100
	v_mul_f32_e32 v110, v29, v1
	v_mul_f32_e32 v1, 0x45800000, v9
	v_mul_f32_e32 v76, v56, v100
	v_mul_f32_e32 v77, v57, v101
	v_mul_f32_e32 v56, v56, v78
	v_mul_f32_e32 v57, v57, v79
	v_mul_f32_e32 v78, v126, v120
	v_mul_f32_e32 v79, v126, v121
	v_mov_b32_e32 v61, v44
	v_cndmask_b32_e32 v148, v9, v1, vcc
	v_mul_f32_e32 v1, 0x45800000, v25
	v_mul_f32_e32 v60, v60, v78
	v_mul_f32_e32 v61, v61, v79
	v_cndmask_b32_e64 v146, v25, v1, s[0:1]
	s_waitcnt vmcnt(0)
	v_mul_f32_e32 v78, v60, v102
	v_mul_f32_e32 v79, v61, v103
	v_mov_b32_e32 v80, v103
	v_mov_b32_e32 v81, v102
	v_cndmask_b32_e64 v64, v202, 1.0, s[56:57]
	v_mul_f32_e32 v60, v60, v80
	v_mul_f32_e32 v61, v61, v81
	v_or_b32_e32 v80, 0x100, v144
	v_mov_b32_e32 v81, v145
	v_lshl_add_u64 v[82:83], s[6:7], 0, v[80:81]
	v_lshl_add_u64 v[80:81], s[8:9], 0, v[80:81]
	s_waitcnt vmcnt(8)
	v_mov_b32_e32 v1, v161
	v_mov_b32_e32 v9, v162
	v_or_b32_e32 v80, 0x140, v144
	v_mov_b32_e32 v81, v145
	v_lshl_add_u64 v[82:83], s[6:7], 0, v[80:81]
	v_lshl_add_u64 v[80:81], s[8:9], 0, v[80:81]
	v_or_b32_e32 v84, 0x180, v144
	v_mov_b32_e32 v85, v145
	v_lshl_add_u64 v[86:87], s[6:7], 0, v[84:85]
	v_lshl_add_u64 v[84:85], s[8:9], 0, v[84:85]
	v_mov_b32_e32 v25, v185
	v_mov_b32_e32 v29, v186
	v_mov_b32_e32 v40, v187
	v_mov_b32_e32 v44, v207
	v_or_b32_e32 v80, 0x1c0, v144
	v_mov_b32_e32 v81, v145
	v_lshl_add_u64 v[82:83], s[6:7], 0, v[80:81]
	v_lshl_add_u64 v[80:81], s[8:9], 0, v[80:81]
	v_mov_b32_e32 v89, v212
	v_mov_b32_e32 v93, v213
	global_load_dword v161, v144, s[6:7] offset:768
	global_load_dword v162, v144, s[8:9] offset:768
	global_load_dword v185, v144, s[6:7] offset:832
	global_load_dword v186, v144, s[8:9] offset:832
	global_load_dword v187, v144, s[6:7] offset:896
	global_load_dword v207, v144, s[8:9] offset:896
	global_load_dword v212, v144, s[6:7] offset:960
	global_load_dword v213, v144, s[8:9] offset:960
	v_mov_b32_e32 v82, v33
	v_mov_b32_e32 v84, v37
	v_mov_b32_e32 v80, v49
	v_mov_b32_e32 v86, v53
	v_mov_b32_e32 v90, v77
	v_mov_b32_e32 v94, v57
	v_mov_b32_e32 v96, v79
	v_mov_b32_e32 v98, v61
	v_mul_f32_e32 v33, v204, v1
	v_mul_f32_e32 v83, v127, v9
	v_mul_f32_e32 v81, v127, v1
	v_mul_f32_e32 v49, v204, v9
	v_add_f32_e32 v32, v32, v82
	v_add_f32_e32 v33, v33, v83
	v_add_f32_e64 v48, v80, -v48
	v_add_f32_e64 v49, v81, -v49
	v_mul_f32_e32 v37, v104, v25
	v_mul_f32_e32 v85, v150, v29
	v_mul_f32_e32 v87, v150, v25
	v_mul_f32_e32 v53, v104, v29
	v_mul_f32_e32 v91, v151, v40
	v_mul_f32_e32 v77, v105, v44
	v_mul_f32_e32 v95, v151, v44
	v_mul_f32_e32 v57, v105, v40
	v_mul_f32_e32 v97, v203, v89
	v_mul_f32_e32 v79, v106, v93
	v_mul_f32_e32 v99, v203, v93
	v_mul_f32_e32 v61, v106, v89
	v_add_f32_e32 v36, v36, v84
	v_add_f32_e32 v37, v37, v85
	v_add_f32_e32 v56, v56, v94
	v_add_f32_e32 v57, v57, v95
	v_add_f32_e32 v60, v60, v98
	v_add_f32_e32 v61, v61, v99
	v_mul_f32_e32 v84, v64, v32
	v_mul_f32_e32 v85, v64, v33
	v_add_f32_e64 v32, v86, -v52
	v_add_f32_e64 v33, v87, -v53
	v_mul_f32_e32 v86, v64, v36
	v_mul_f32_e32 v87, v64, v37
	v_add_f32_e64 v36, v90, -v76
	v_add_f32_e64 v37, v91, -v77
	v_add_f32_e64 v52, v96, -v78
	v_add_f32_e64 v53, v97, -v79
	v_mul_f32_e32 v90, v64, v56
	v_mul_f32_e32 v91, v64, v57
	v_mul_f32_e32 v76, v64, v48
	v_mul_f32_e32 v77, v64, v49
	v_mul_f32_e32 v78, v64, v32
	v_mul_f32_e32 v79, v64, v33
	v_mul_f32_e32 v80, v64, v36
	v_mul_f32_e32 v81, v64, v37
	v_mul_f32_e32 v82, v64, v52
	v_mul_f32_e32 v83, v64, v53
	v_mul_f32_e32 v94, v64, v60
	v_mul_f32_e32 v95, v64, v61
	v_or_b32_e32 v32, 0x200, v144
	v_mov_b32_e32 v33, v145
	v_or_b32_e32 v48, 0x240, v144
	v_mov_b32_e32 v49, v145
	v_lshl_add_u64 v[36:37], s[6:7], 0, v[32:33]
	v_lshl_add_u64 v[32:33], s[8:9], 0, v[32:33]
	v_lshl_add_u64 v[52:53], s[6:7], 0, v[48:49]
	v_lshl_add_u64 v[48:49], s[8:9], 0, v[48:49]
	v_or_b32_e32 v56, 0x280, v144
	v_mov_b32_e32 v57, v145
	v_lshl_add_u64 v[60:61], s[6:7], 0, v[56:57]
	v_lshl_add_u64 v[56:57], s[8:9], 0, v[56:57]
	s_waitcnt vmcnt(8)
	v_mov_b32_e32 v37, v66
	s_nop 0
	v_mov_b32_e32 v36, v67
	s_nop 0
	v_mov_b32_e32 v33, v68
	v_mov_b32_e32 v32, v69
	s_nop 0
	v_mov_b32_e32 v49, v71
	v_mov_b32_e32 v48, v74
	v_or_b32_e32 v52, 0x2c0, v144
	v_mov_b32_e32 v53, v145
	v_lshl_add_u64 v[56:57], s[6:7], 0, v[52:53]
	v_lshl_add_u64 v[52:53], s[8:9], 0, v[52:53]
	v_mov_b32_e32 v57, v75
	s_nop 0
	v_mov_b32_e32 v56, v160
	global_load_dword v66, v144, s[10:11]
	global_load_dword v67, v144, s[12:13]
	global_load_dword v68, v144, s[10:11] offset:64
	global_load_dword v69, v144, s[12:13] offset:64
	global_load_dword v71, v144, s[10:11] offset:128
	global_load_dword v74, v144, s[12:13] offset:128
	global_load_dword v75, v144, s[10:11] offset:192
	global_load_dword v160, v144, s[12:13] offset:192
	v_mul_f32_e32 v52, v92, v142
	v_mul_f32_e32 v53, v92, v143
	v_mov_b32_e32 v60, v50
	v_mov_b32_e32 v61, v34
	v_mul_f32_e32 v96, v92, v140
	v_mul_f32_e32 v97, v92, v141
	v_mov_b32_e32 v98, v54
	v_mov_b32_e32 v99, v38
	v_mul_f32_e32 v100, v92, v124
	v_mul_f32_e32 v101, v92, v125
	v_mov_b32_e32 v102, v58
	v_mov_b32_e32 v103, v42
	v_mul_f32_e32 v93, v92, v121
	v_mul_f32_e32 v92, v92, v120
	v_mov_b32_e32 v104, v62
	v_mov_b32_e32 v105, v46
	v_mul_f32_e32 v52, v60, v52
	v_mul_f32_e32 v53, v61, v53
	v_mul_f32_e32 v60, v98, v96
	v_mul_f32_e32 v61, v99, v97
	v_mul_f32_e32 v96, v102, v100
	v_mul_f32_e32 v97, v103, v101
	v_mul_f32_e32 v92, v104, v92
	v_mul_f32_e32 v93, v105, v93
	v_mov_b32_e32 v100, v37
	v_mul_f32_e32 v98, v52, v36
	v_mul_f32_e32 v99, v53, v37
	v_mov_b32_e32 v101, v36
	v_mul_f32_e32 v102, v60, v32
	v_mul_f32_e32 v103, v61, v33
	v_mov_b32_e32 v36, v33
	v_mov_b32_e32 v37, v32
	v_mul_f32_e32 v104, v96, v48
	v_mul_f32_e32 v105, v97, v49
	v_mov_b32_e32 v32, v49
	v_mov_b32_e32 v33, v48
	v_mov_b32_e32 v106, v57
	v_mov_b32_e32 v107, v56
	v_mul_f32_e32 v106, v92, v106
	v_mul_f32_e32 v107, v93, v107
	v_mul_f32_e32 v48, v92, v56
	v_mul_f32_e32 v49, v93, v57
	v_mul_f32_e32 v52, v52, v100
	v_mul_f32_e32 v53, v53, v101
	v_mul_f32_e32 v56, v60, v36
	v_mul_f32_e32 v57, v61, v37
	v_mul_f32_e32 v60, v96, v32
	v_mul_f32_e32 v61, v97, v33
	v_or_b32_e32 v32, 0x300, v144
	v_mov_b32_e32 v33, v145
	v_or_b32_e32 v92, 0x340, v144
	v_mov_b32_e32 v93, v145
	v_lshl_add_u64 v[36:37], s[6:7], 0, v[32:33]
	v_lshl_add_u64 v[96:97], s[6:7], 0, v[92:93]
	v_lshl_add_u64 v[92:93], s[8:9], 0, v[92:93]
	v_or_b32_e32 v100, 0x380, v144
	v_mov_b32_e32 v101, v145
	v_lshl_add_u64 v[32:33], s[8:9], 0, v[32:33]
	v_lshl_add_u64 v[112:113], s[6:7], 0, v[100:101]
	v_lshl_add_u64 v[100:101], s[8:9], 0, v[100:101]
	s_waitcnt vmcnt(8)
	v_mov_b32_e32 v114, v161
	v_mov_b32_e32 v115, v162
	s_nop 0
	v_mov_b32_e32 v96, v185
	s_nop 0
	v_mov_b32_e32 v97, v186
	s_nop 0
	v_mov_b32_e32 v92, v187
	v_mov_b32_e32 v93, v207
	v_or_b32_e32 v32, 0x3c0, v144
	v_mov_b32_e32 v33, v145
	v_lshl_add_u64 v[36:37], s[6:7], 0, v[32:33]
	v_lshl_add_u64 v[32:33], s[8:9], 0, v[32:33]
	v_mov_b32_e32 v112, v212
	v_mov_b32_e32 v113, v213
	global_load_dword v161, v144, s[10:11] offset:256
	global_load_dword v162, v144, s[12:13] offset:256
	global_load_dword v185, v144, s[10:11] offset:320
	global_load_dword v186, v144, s[12:13] offset:320
	global_load_dword v187, v144, s[10:11] offset:384
	global_load_dword v207, v144, s[12:13] offset:384
	global_load_dword v212, v144, s[10:11] offset:448
	global_load_dword v213, v144, s[12:13] offset:448
	v_mov_b32_e32 v32, v143
	v_mov_b32_e32 v33, v142
	v_mov_b32_e32 v50, v35
	v_mov_b32_e32 v34, v141
	v_mov_b32_e32 v35, v140
	v_mov_b32_e32 v54, v39
	v_mov_b32_e32 v36, v125
	v_mov_b32_e32 v37, v124
	v_mov_b32_e32 v38, v121
	v_mov_b32_e32 v39, v120
	v_mul_f32_e32 v116, v88, v32
	v_mul_f32_e32 v117, v88, v33
	v_mov_b32_e32 v58, v43
	v_mov_b32_e32 v62, v47
	v_mul_f32_e32 v118, v88, v34
	v_mul_f32_e32 v119, v88, v35
	v_mul_f32_e32 v122, v88, v36
	v_mul_f32_e32 v123, v88, v37
	v_mul_f32_e32 v89, v88, v39
	v_mul_f32_e32 v88, v88, v38
	v_mul_f32_e32 v50, v50, v116
	v_mul_f32_e32 v51, v51, v117
	v_mul_f32_e32 v54, v54, v118
	v_mul_f32_e32 v55, v55, v119
	v_mul_f32_e32 v58, v58, v122
	v_mul_f32_e32 v59, v59, v123
	v_mul_f32_e32 v62, v62, v88
	v_mul_f32_e32 v63, v63, v89
	v_mov_b32_e32 v42, v52
	v_mov_b32_e32 v100, v60
	v_mov_b32_e32 v46, v56
	v_mov_b32_e32 v117, v114
	v_mov_b32_e32 v116, v115
	v_mul_f32_e32 v88, v50, v114
	v_mul_f32_e32 v89, v51, v115
	v_mul_f32_e32 v50, v50, v116
	v_mul_f32_e32 v51, v51, v117
	v_mov_b32_e32 v123, v92
	v_mov_b32_e32 v122, v93
	v_mul_f32_e32 v114, v54, v96
	v_mul_f32_e32 v115, v55, v97
	v_mov_b32_e32 v118, v97
	v_mov_b32_e32 v119, v96
	v_mul_f32_e32 v96, v58, v92
	v_mul_f32_e32 v97, v59, v93
	v_mul_f32_e32 v58, v58, v122
	v_mul_f32_e32 v59, v59, v123
	v_mov_b32_e32 v43, v51
	v_pk_mov_b32 v[50:51], v[52:53], v[50:51] op_sel:[1,0]
	v_mul_f32_e32 v54, v54, v118
	v_mul_f32_e32 v55, v55, v119
	v_mov_b32_e32 v101, v59
	v_pk_mov_b32 v[58:59], v[60:61], v[58:59] op_sel:[1,0]
	v_add_f32_e32 v42, v42, v50
	v_add_f32_e32 v43, v43, v51
	v_mov_b32_e32 v47, v55
	v_pk_mov_b32 v[54:55], v[56:57], v[54:55] op_sel:[1,0]
	v_add_f32_e32 v50, v100, v58
	v_add_f32_e32 v51, v101, v59
	v_mul_f32_e32 v100, v64, v42
	v_mul_f32_e32 v101, v64, v43
	v_mov_b32_e32 v42, v113
	v_mov_b32_e32 v43, v112
	v_mul_f32_e32 v92, v62, v112
	v_mul_f32_e32 v93, v63, v113
	v_pk_mov_b32 v[126:127], v[98:99], v[88:89] op_sel:[1,0]
	v_mov_b32_e32 v99, v89
	v_pk_mov_b32 v[88:89], v[102:103], v[114:115] op_sel:[1,0]
	v_mov_b32_e32 v103, v115
	v_add_f32_e32 v46, v46, v54
	v_add_f32_e32 v47, v47, v55
	v_mul_f32_e32 v42, v62, v42
	v_mul_f32_e32 v43, v63, v43
	v_pk_mov_b32 v[114:115], v[104:105], v[96:97] op_sel:[1,0]
	v_mov_b32_e32 v105, v97
	v_pk_mov_b32 v[96:97], v[48:49], v[92:93] op_sel:[1,0]
	v_mov_b32_e32 v49, v93
	v_add_f32_e64 v52, v88, -v102
	v_add_f32_e64 v53, v89, -v103
	v_mul_f32_e32 v102, v64, v46
	v_mul_f32_e32 v103, v64, v47
	v_mov_b32_e32 v46, v106
	v_mov_b32_e32 v47, v43
	v_pk_mov_b32 v[42:43], v[106:107], v[42:43] op_sel:[1,0]
	v_add_f32_e64 v92, v126, -v98
	v_add_f32_e64 v93, v127, -v99
	v_add_f32_e64 v56, v114, -v104
	v_add_f32_e64 v57, v115, -v105
	v_add_f32_e64 v48, v96, -v48
	v_add_f32_e64 v49, v97, -v49
	v_add_f32_e32 v42, v46, v42
	v_add_f32_e32 v43, v47, v43
	v_mul_f32_e32 v88, v64, v92
	v_mul_f32_e32 v89, v64, v93
	v_mul_f32_e32 v92, v64, v52
	v_mul_f32_e32 v93, v64, v53
	v_mul_f32_e32 v96, v64, v56
	v_mul_f32_e32 v97, v64, v57
	v_mul_f32_e32 v104, v64, v50
	v_mul_f32_e32 v105, v64, v51
	v_mul_f32_e32 v98, v64, v48
	v_mul_f32_e32 v99, v64, v49
	v_mul_f32_e32 v106, v64, v42
	v_mul_f32_e32 v107, v64, v43
	v_or_b32_e32 v42, 0x1000, v144
	v_mov_b32_e32 v43, v145
	v_or_b32_e32 v48, 0x1040, v144
	v_mov_b32_e32 v49, v145
	v_lshl_add_u64 v[46:47], s[6:7], 0, v[42:43]
	v_lshl_add_u64 v[42:43], s[8:9], 0, v[42:43]
	v_lshl_add_u64 v[50:51], s[6:7], 0, v[48:49]
	v_lshl_add_u64 v[48:49], s[8:9], 0, v[48:49]
	v_or_b32_e32 v52, 0x1080, v144
	v_mov_b32_e32 v53, v145
	v_lshl_add_u64 v[54:55], s[6:7], 0, v[52:53]
	v_lshl_add_u64 v[52:53], s[8:9], 0, v[52:53]
	s_waitcnt vmcnt(8)
	v_mov_b32_e32 v47, v66
	s_nop 0
	v_mov_b32_e32 v46, v67
	s_nop 0
	v_mov_b32_e32 v43, v68
	v_mov_b32_e32 v42, v69
	s_nop 0
	v_mov_b32_e32 v49, v71
	v_mov_b32_e32 v48, v74
	v_or_b32_e32 v50, 0x10c0, v144
	v_mov_b32_e32 v51, v145
	v_lshl_add_u64 v[52:53], s[6:7], 0, v[50:51]
	v_lshl_add_u64 v[50:51], s[8:9], 0, v[50:51]
	v_mov_b32_e32 v53, v75
	s_nop 0
	v_mov_b32_e32 v52, v160
	global_load_dword v66, v144, s[10:11] offset:512
	global_load_dword v67, v144, s[12:13] offset:512
	global_load_dword v68, v144, s[10:11] offset:576
	global_load_dword v69, v144, s[12:13] offset:576
	global_load_dword v71, v144, s[10:11] offset:640
	global_load_dword v74, v144, s[12:13] offset:640
	global_load_dword v75, v144, s[10:11] offset:704
	global_load_dword v160, v144, s[12:13] offset:704
	v_mul_f32_e32 v50, v108, v142
	v_mul_f32_e32 v51, v108, v143
	v_mov_b32_e32 v1, v4
	v_mul_f32_e32 v54, v108, v140
	v_mul_f32_e32 v55, v108, v141
	v_mov_b32_e32 v9, v12
	v_mul_f32_e32 v56, v108, v124
	v_mul_f32_e32 v57, v108, v125
	v_mov_b32_e32 v25, v16
	v_mul_f32_e32 v58, v108, v120
	v_mul_f32_e32 v59, v108, v121
	v_mov_b32_e32 v29, v20
	v_mul_f32_e32 v0, v0, v50
	v_mul_f32_e32 v1, v1, v51
	v_mul_f32_e32 v8, v8, v54
	v_mul_f32_e32 v9, v9, v55
	v_mul_f32_e32 v24, v24, v56
	v_mul_f32_e32 v25, v25, v57
	v_mul_f32_e32 v28, v28, v58
	v_mul_f32_e32 v29, v29, v59
	v_mov_b32_e32 v54, v47
	v_mov_b32_e32 v55, v46
	v_mov_b32_e32 v56, v43
	v_mov_b32_e32 v57, v42
	v_mov_b32_e32 v58, v49
	v_mov_b32_e32 v59, v48
	v_mul_f32_e32 v50, v0, v46
	v_mul_f32_e32 v51, v1, v47
	v_mul_f32_e32 v46, v8, v42
	v_mul_f32_e32 v47, v9, v43
	v_mul_f32_e32 v42, v24, v48
	v_mul_f32_e32 v43, v25, v49
	v_mov_b32_e32 v60, v53
	v_mov_b32_e32 v61, v52
	v_mul_f32_e32 v48, v28, v52
	v_mul_f32_e32 v49, v29, v53
	v_mul_f32_e32 v0, v0, v54
	v_mul_f32_e32 v1, v1, v55
	v_mul_f32_e32 v8, v8, v56
	v_mul_f32_e32 v9, v9, v57
	v_mul_f32_e32 v24, v24, v58
	v_mul_f32_e32 v25, v25, v59
	v_mul_f32_e32 v28, v28, v60
	v_mul_f32_e32 v29, v29, v61
	v_or_b32_e32 v52, 0x1100, v144
	v_mov_b32_e32 v53, v145
	v_lshl_add_u64 v[54:55], s[6:7], 0, v[52:53]
	v_lshl_add_u64 v[52:53], s[8:9], 0, v[52:53]
	s_waitcnt vmcnt(8)
	v_mov_b32_e32 v60, v161
	v_mov_b32_e32 v61, v162
	v_or_b32_e32 v52, 0x1140, v144
	v_mov_b32_e32 v53, v145
	v_or_b32_e32 v56, 0x1180, v144
	v_mov_b32_e32 v57, v145
	v_lshl_add_u64 v[54:55], s[6:7], 0, v[52:53]
	v_lshl_add_u64 v[52:53], s[8:9], 0, v[52:53]
	v_lshl_add_u64 v[58:59], s[6:7], 0, v[56:57]
	v_lshl_add_u64 v[56:57], s[8:9], 0, v[56:57]
	v_mov_b32_e32 v62, v185
	v_mov_b32_e32 v63, v186
	s_nop 0
	v_mov_b32_e32 v58, v187
	s_nop 0
	v_mov_b32_e32 v56, v207
	v_or_b32_e32 v52, 0x11c0, v144
	v_mov_b32_e32 v53, v145
	v_lshl_add_u64 v[54:55], s[6:7], 0, v[52:53]
	v_lshl_add_u64 v[52:53], s[8:9], 0, v[52:53]
	v_mov_b32_e32 v57, v212
	v_mov_b32_e32 v59, v213
	global_load_dword v161, v144, s[10:11] offset:768
	global_load_dword v162, v144, s[12:13] offset:768
	global_load_dword v185, v144, s[10:11] offset:832
	global_load_dword v186, v144, s[12:13] offset:832
	global_load_dword v187, v144, s[10:11] offset:896
	global_load_dword v207, v144, s[12:13] offset:896
	global_load_dword v212, v144, s[10:11] offset:960
	global_load_dword v213, v144, s[12:13] offset:960
	v_mov_b32_e32 v52, v51
	v_mov_b32_e32 v40, v1
	v_mov_b32_e32 v44, v9
	v_mov_b32_e32 v4, v25
	v_mov_b32_e32 v16, v49
	v_mov_b32_e32 v20, v47
	v_mov_b32_e32 v54, v43
	v_mov_b32_e32 v12, v29
	v_mul_f32_e32 v53, v41, v60
	v_mul_f32_e32 v51, v21, v61
	v_mul_f32_e32 v41, v41, v61
	v_mul_f32_e32 v1, v21, v60
	v_add_f32_e32 v0, v0, v40
	v_add_f32_e32 v1, v1, v41
	v_mul_f32_e32 v21, v45, v62
	v_mul_f32_e32 v45, v45, v63
	v_mul_f32_e32 v9, v109, v62
	v_mul_f32_e32 v55, v5, v58
	v_mul_f32_e32 v49, v17, v56
	v_mul_f32_e32 v5, v5, v56
	v_mul_f32_e32 v25, v17, v58
	v_mul_f32_e32 v47, v109, v63
	v_mul_f32_e32 v56, v110, v59
	v_mul_f32_e32 v17, v13, v57
	v_mul_f32_e32 v13, v13, v59
	v_mul_f32_e32 v29, v110, v57
	v_add_f32_e32 v8, v8, v44
	v_add_f32_e32 v9, v9, v45
	v_mov_b32_e32 v43, v49
	v_add_f32_e32 v4, v24, v4
	v_add_f32_e32 v5, v25, v5
	v_mov_b32_e32 v49, v56
	v_add_f32_e32 v12, v28, v12
	v_add_f32_e32 v13, v29, v13
	v_add_f32_e64 v24, v52, -v50
	v_add_f32_e64 v25, v53, -v51
	v_mul_f32_e32 v116, v64, v0
	v_mul_f32_e32 v117, v64, v1
	v_add_f32_e64 v0, v20, -v46
	v_add_f32_e64 v1, v21, -v47
	v_mul_f32_e32 v118, v64, v8
	v_mul_f32_e32 v119, v64, v9
	v_add_f32_e64 v8, v54, -v42
	v_add_f32_e64 v9, v55, -v43
	v_mul_f32_e32 v122, v64, v4
	v_mul_f32_e32 v123, v64, v5
	v_add_f32_e64 v4, v16, -v48
	v_add_f32_e64 v5, v17, -v49
	v_mul_f32_e32 v108, v64, v24
	v_mul_f32_e32 v109, v64, v25
	v_mul_f32_e32 v110, v64, v0
	v_mul_f32_e32 v111, v64, v1
	v_mul_f32_e32 v112, v64, v8
	v_mul_f32_e32 v113, v64, v9
	v_mul_f32_e32 v114, v64, v4
	v_mul_f32_e32 v115, v64, v5
	v_mul_f32_e32 v126, v64, v12
	v_mul_f32_e32 v127, v64, v13
	v_or_b32_e32 v0, 0x1200, v144
	v_mov_b32_e32 v1, v145
	v_or_b32_e32 v8, 0x1240, v144
	v_mov_b32_e32 v9, v145
	v_lshl_add_u64 v[4:5], s[6:7], 0, v[0:1]
	v_lshl_add_u64 v[0:1], s[8:9], 0, v[0:1]
	v_lshl_add_u64 v[12:13], s[6:7], 0, v[8:9]
	v_lshl_add_u64 v[8:9], s[8:9], 0, v[8:9]
	v_or_b32_e32 v16, 0x1280, v144
	v_mov_b32_e32 v17, v145
	v_lshl_add_u64 v[20:21], s[6:7], 0, v[16:17]
	v_lshl_add_u64 v[16:17], s[8:9], 0, v[16:17]
	s_waitcnt vmcnt(8)
	v_mov_b32_e32 v5, v66
	s_nop 0
	v_mov_b32_e32 v4, v67
	s_nop 0
	v_mov_b32_e32 v1, v68
	v_mov_b32_e32 v0, v69
	s_nop 0
	v_mov_b32_e32 v9, v71
	v_mov_b32_e32 v8, v74
	v_or_b32_e32 v12, 0x12c0, v144
	v_mov_b32_e32 v13, v145
	v_lshl_add_u64 v[16:17], s[6:7], 0, v[12:13]
	v_lshl_add_u64 v[12:13], s[8:9], 0, v[12:13]
	v_mov_b32_e32 v17, v75
	s_nop 0
	v_mov_b32_e32 v16, v160
	v_mul_f32_e32 v12, v148, v142
	v_mul_f32_e32 v13, v148, v143
	v_mov_b32_e32 v20, v2
	v_mov_b32_e32 v21, v6
	v_mul_f32_e32 v24, v148, v140
	v_mul_f32_e32 v25, v148, v141
	v_mov_b32_e32 v28, v10
	v_mov_b32_e32 v29, v14
	v_mul_f32_e32 v40, v148, v124
	v_mul_f32_e32 v41, v148, v125
	v_mov_b32_e32 v42, v26
	v_mov_b32_e32 v43, v18
	v_mul_f32_e32 v44, v148, v120
	v_mul_f32_e32 v45, v148, v121
	v_mov_b32_e32 v46, v30
	v_mov_b32_e32 v47, v22
	v_mul_f32_e32 v12, v20, v12
	v_mul_f32_e32 v13, v21, v13
	v_mul_f32_e32 v20, v28, v24
	v_mul_f32_e32 v21, v29, v25
	v_mul_f32_e32 v24, v42, v40
	v_mul_f32_e32 v25, v43, v41
	v_mul_f32_e32 v28, v46, v44
	v_mul_f32_e32 v29, v47, v45
	v_mov_b32_e32 v42, v5
	v_mov_b32_e32 v43, v4
	v_mov_b32_e32 v44, v1
	v_mov_b32_e32 v45, v0
	v_mov_b32_e32 v46, v9
	v_mov_b32_e32 v47, v8
	v_mul_f32_e32 v40, v12, v4
	v_mul_f32_e32 v41, v13, v5
	v_mul_f32_e32 v4, v20, v0
	v_mul_f32_e32 v5, v21, v1
	v_mul_f32_e32 v0, v24, v8
	v_mul_f32_e32 v1, v25, v9
	v_mov_b32_e32 v48, v17
	v_mov_b32_e32 v49, v16
	v_mul_f32_e32 v8, v28, v16
	v_mul_f32_e32 v9, v29, v17
	v_mul_f32_e32 v12, v12, v42
	v_mul_f32_e32 v13, v13, v43
	v_mul_f32_e32 v16, v20, v44
	v_mul_f32_e32 v17, v21, v45
	v_mul_f32_e32 v20, v24, v46
	v_mul_f32_e32 v21, v25, v47
	v_mul_f32_e32 v24, v28, v48
	v_mul_f32_e32 v25, v29, v49
	v_or_b32_e32 v28, 0x1300, v144
	v_mov_b32_e32 v29, v145
	v_or_b32_e32 v44, 0x1340, v144
	v_mov_b32_e32 v45, v145
	v_lshl_add_u64 v[42:43], s[6:7], 0, v[28:29]
	v_lshl_add_u64 v[28:29], s[8:9], 0, v[28:29]
	v_lshl_add_u64 v[46:47], s[6:7], 0, v[44:45]
	v_lshl_add_u64 v[44:45], s[8:9], 0, v[44:45]
	v_or_b32_e32 v48, 0x1380, v144
	v_mov_b32_e32 v49, v145
	v_or_b32_e32 v144, 0x13c0, v144
	v_lshl_add_u64 v[50:51], s[6:7], 0, v[48:49]
	v_lshl_add_u64 v[48:49], s[8:9], 0, v[48:49]
	s_waitcnt vmcnt(0)
	v_mov_b32_e32 v42, v161
	s_nop 0
	v_mov_b32_e32 v43, v162
	s_nop 0
	v_mov_b32_e32 v28, v185
	v_mov_b32_e32 v29, v186
	s_nop 0
	v_mov_b32_e32 v44, v187
	v_mov_b32_e32 v45, v207
	v_lshl_add_u64 v[46:47], s[6:7], 0, v[144:145]
	v_lshl_add_u64 v[48:49], s[8:9], 0, v[144:145]
	v_mov_b32_e32 v46, v212
	s_nop 0
	v_mov_b32_e32 v47, v213
	ds_read_b32 v66, v129 offset:45056
	ds_read_b32 v67, v129 offset:45060
	ds_read_b32 v68, v129 offset:45064
	ds_read_b32 v69, v129 offset:45068
	ds_read_b32 v71, v129 offset:49152
	ds_read_b32 v74, v129 offset:49156
	ds_read_b32 v75, v129 offset:49160
	ds_read_b32 v160, v129 offset:49164
	ds_read_b32 v161, v129 offset:53248
	ds_read_b32 v162, v129 offset:53252
	ds_read_b32 v185, v129 offset:53256
	ds_read_b32 v186, v129 offset:53260
	ds_read_b32 v187, v129 offset:57344
	ds_read_b32 v207, v129 offset:57348
	ds_read_b32 v212, v129 offset:57352
	ds_read_b32 v213, v129 offset:57356
	s_waitcnt lgkmcnt(0)
	v_mul_f32_e32 v32, v32, v146
	v_mul_f32_e32 v33, v33, v146
	v_mov_b32_e32 v2, v7
	v_mul_f32_e32 v34, v34, v146
	v_mul_f32_e32 v35, v35, v146
	v_mov_b32_e32 v10, v15
	v_mul_f32_e32 v36, v36, v146
	v_mul_f32_e32 v37, v37, v146
	v_mov_b32_e32 v26, v19
	v_mul_f32_e32 v38, v38, v146
	v_mul_f32_e32 v39, v39, v146
	v_mov_b32_e32 v30, v23
	v_mul_f32_e32 v2, v2, v32
	v_mul_f32_e32 v3, v3, v33
	v_mul_f32_e32 v10, v10, v34
	v_mul_f32_e32 v11, v11, v35
	v_mul_f32_e32 v26, v26, v36
	v_mul_f32_e32 v27, v27, v37
	v_mul_f32_e32 v30, v30, v38
	v_mul_f32_e32 v31, v31, v39
	v_mov_b32_e32 v6, v12
	v_mov_b32_e32 v14, v16
	v_mov_b32_e32 v18, v20
	v_mov_b32_e32 v22, v24
	v_mov_b32_e32 v35, v42
	v_mul_f32_e32 v32, v2, v42
	v_mul_f32_e32 v33, v3, v43
	v_mov_b32_e32 v34, v43
	v_mul_f32_e32 v36, v10, v28
	v_mul_f32_e32 v37, v11, v29
	v_mov_b32_e32 v38, v29
	v_mov_b32_e32 v39, v28
	v_mul_f32_e32 v28, v26, v44
	v_mul_f32_e32 v29, v27, v45
	v_mov_b32_e32 v42, v45
	v_mov_b32_e32 v43, v44
	v_mov_b32_e32 v48, v47
	v_mov_b32_e32 v49, v46
	v_mul_f32_e32 v44, v30, v46
	v_mul_f32_e32 v45, v31, v47
	v_pk_mov_b32 v[46:47], v[40:41], v[32:33] op_sel:[1,0]
	v_mov_b32_e32 v41, v33
	v_mul_f32_e32 v2, v2, v34
	v_mul_f32_e32 v3, v3, v35
	v_pk_mov_b32 v[32:33], v[4:5], v[36:37] op_sel:[1,0]
	v_mov_b32_e32 v5, v37
	v_mul_f32_e32 v10, v10, v38
	v_mul_f32_e32 v11, v11, v39
	v_pk_mov_b32 v[34:35], v[0:1], v[28:29] op_sel:[1,0]
	v_mov_b32_e32 v1, v29
	v_mul_f32_e32 v26, v26, v42
	v_mul_f32_e32 v27, v27, v43
	v_mul_f32_e32 v30, v30, v48
	v_mul_f32_e32 v31, v31, v49
	v_pk_mov_b32 v[28:29], v[8:9], v[44:45] op_sel:[1,0]
	v_mov_b32_e32 v9, v45
	v_mov_b32_e32 v7, v3
	v_pk_mov_b32 v[2:3], v[12:13], v[2:3] op_sel:[1,0]
	v_add_f32_e64 v4, v32, -v4
	v_add_f32_e64 v5, v33, -v5
	v_mov_b32_e32 v15, v11
	v_pk_mov_b32 v[10:11], v[16:17], v[10:11] op_sel:[1,0]
	v_add_f32_e64 v0, v34, -v0
	v_add_f32_e64 v1, v35, -v1
	v_mov_b32_e32 v19, v27
	v_pk_mov_b32 v[12:13], v[20:21], v[26:27] op_sel:[1,0]
	v_mov_b32_e32 v23, v31
	v_pk_mov_b32 v[16:17], v[24:25], v[30:31] op_sel:[1,0]
	v_add_f32_e64 v36, v46, -v40
	v_add_f32_e64 v37, v47, -v41
	v_add_f32_e64 v8, v28, -v8
	v_add_f32_e64 v9, v29, -v9
	v_add_f32_e32 v2, v6, v2
	v_add_f32_e32 v3, v7, v3
	v_mul_f32_e32 v124, v64, v4
	v_mul_f32_e32 v125, v64, v5
	v_add_f32_e32 v4, v14, v10
	v_add_f32_e32 v5, v15, v11
	v_mul_f32_e32 v140, v64, v0
	v_mul_f32_e32 v141, v64, v1
	v_add_f32_e32 v0, v18, v12
	v_add_f32_e32 v1, v19, v13
	v_add_f32_e32 v6, v22, v16
	v_add_f32_e32 v7, v23, v17
	v_mul_f32_e32 v120, v64, v36
	v_mul_f32_e32 v121, v64, v37
	v_mul_f32_e32 v142, v64, v8
	v_mul_f32_e32 v143, v64, v9
	v_mul_f32_e32 v144, v64, v2
	v_mul_f32_e32 v145, v64, v3
	v_mul_f32_e32 v146, v64, v4
	v_mul_f32_e32 v147, v64, v5
	v_mul_f32_e32 v148, v64, v0
	v_mul_f32_e32 v149, v64, v1
	v_mul_f32_e32 v150, v64, v6
	v_mul_f32_e32 v151, v64, v7
	s_branch .Lmy_rp_join
.Lmy_rp_p2:
	s_add_u32 s10, s6, 0x1000
	s_addc_u32 s11, s7, 0
	s_add_u32 s12, s8, 0x1000
	s_addc_u32 s13, s9, 0
	global_load_dword v188, v144, s[6:7] offset:256
	global_load_dword v189, v144, s[8:9] offset:256
	global_load_dword v190, v144, s[6:7] offset:320
	global_load_dword v191, v144, s[8:9] offset:320
	global_load_dword v208, v144, s[6:7] offset:384
	global_load_dword v209, v144, s[8:9] offset:384
	global_load_dword v210, v144, s[6:7] offset:448
	global_load_dword v211, v144, s[8:9] offset:448
	global_load_dword v232, v144, s[6:7] offset:512
	global_load_dword v233, v144, s[8:9] offset:512
	global_load_dword v234, v144, s[6:7] offset:576
	global_load_dword v235, v144, s[8:9] offset:576
	global_load_dword v236, v144, s[6:7] offset:640
	global_load_dword v237, v144, s[8:9] offset:640
	global_load_dword v238, v144, s[6:7] offset:704
	global_load_dword v239, v144, s[8:9] offset:704
	global_load_dword v240, v144, s[6:7] offset:768
	global_load_dword v241, v144, s[8:9] offset:768
	global_load_dword v242, v144, s[6:7] offset:832
	global_load_dword v243, v144, s[8:9] offset:832
	global_load_dword v248, v144, s[6:7] offset:896
	global_load_dword v249, v144, s[8:9] offset:896
	global_load_dword v250, v144, s[6:7] offset:960
	global_load_dword v251, v144, s[8:9] offset:960
	global_load_dword v252, v144, s[10:11]
	global_load_dword v253, v144, s[12:13]
	global_load_dword v254, v144, s[10:11] offset:64
	global_load_dword v255, v144, s[12:13] offset:64
	global_load_dword v66, v144, s[10:11] offset:128
	global_load_dword v67, v144, s[12:13] offset:128
	global_load_dword v68, v144, s[10:11] offset:192
	global_load_dword v69, v144, s[12:13] offset:192
	global_load_dword v71, v144, s[10:11] offset:256
	global_load_dword v74, v144, s[12:13] offset:256
	global_load_dword v75, v144, s[10:11] offset:320
	global_load_dword v160, v144, s[12:13] offset:320
	global_load_dword v161, v144, s[10:11] offset:384
	global_load_dword v162, v144, s[12:13] offset:384
	global_load_dword v185, v144, s[10:11] offset:448
	global_load_dword v186, v144, s[12:13] offset:448
	global_load_dword v187, v144, s[10:11] offset:512
	global_load_dword v207, v144, s[12:13] offset:512
	global_load_dword v212, v144, s[10:11] offset:576
	global_load_dword v213, v144, s[12:13] offset:576
	global_load_dword v214, v144, s[10:11] offset:640
	global_load_dword v216, v144, s[12:13] offset:640
	global_load_dword v218, v144, s[10:11] offset:704
	global_load_dword v220, v144, s[12:13] offset:704
	global_load_dword v222, v144, s[10:11] offset:768
	global_load_dword v224, v144, s[12:13] offset:768
	global_load_dword v226, v144, s[10:11] offset:832
	global_load_dword v228, v144, s[12:13] offset:832
	global_load_dword v230, v144, s[10:11] offset:896
	global_load_dword v231, v144, s[12:13] offset:896
	global_load_dword v244, v144, s[10:11] offset:960
	global_load_dword v245, v144, s[12:13] offset:960
	v_lshl_add_u64 v[84:85], s[6:7], 0, v[144:145]
	v_lshl_add_u64 v[94:95], s[8:9], 0, v[144:145]
	global_load_dword v85, v[84:85], off
	s_nop 0
	global_load_dword v84, v[94:95], off
	v_or_b32_e32 v94, 64, v144
	v_mov_b32_e32 v95, v145
	v_lshl_add_u64 v[96:97], s[6:7], 0, v[94:95]
	v_lshl_add_u64 v[94:95], s[8:9], 0, v[94:95]
	global_load_dword v97, v[96:97], off
	s_nop 0
	global_load_dword v96, v[94:95], off
	v_or_b32_e32 v98, 0x80, v144
	v_mov_b32_e32 v99, v145
	v_lshl_add_u64 v[100:101], s[6:7], 0, v[98:99]
	v_lshl_add_u64 v[98:99], s[8:9], 0, v[98:99]
	global_load_dword v101, v[100:101], off
	s_nop 0
	global_load_dword v100, v[98:99], off
	v_or_b32_e32 v98, 0xc0, v144
	v_mov_b32_e32 v99, v145
	v_lshl_add_u64 v[102:103], s[6:7], 0, v[98:99]
	v_lshl_add_u64 v[98:99], s[8:9], 0, v[98:99]
	global_load_dword v103, v[102:103], off
	s_nop 0
	global_load_dword v102, v[98:99], off
	v_mul_f32_e32 v112, v14, v14
	v_mul_f32_e32 v113, v15, v15
	v_mul_f32_e32 v86, v86, v86
	v_mul_f32_e32 v87, v87, v87
	v_fma_f32 v112, v6, v6, v112
	v_fma_f32 v113, v7, v7, v113
	v_mov_b32_e32 v80, v2
	v_mov_b32_e32 v81, v10
	v_mov_b32_e32 v94, v86
	v_mov_b32_e32 v95, v122
	v_mul_f32_e32 v80, v80, v80
	v_mul_f32_e32 v81, v81, v81
	v_add_f32_e32 v94, v113, v94
	v_add_f32_e32 v95, v112, v95
	v_mov_b32_e32 v122, v87
	v_mov_b32_e32 v82, v26
	v_mov_b32_e32 v83, v30
	v_add_f32_e32 v86, v94, v122
	v_add_f32_e32 v87, v95, v123
	v_mov_b32_e32 v94, v90
	v_mov_b32_e32 v95, v80
	v_mul_f32_e32 v82, v82, v82
	v_mul_f32_e32 v83, v83, v83
	v_add_f32_e32 v86, v86, v94
	v_add_f32_e32 v87, v87, v95
	v_mov_b32_e32 v80, v91
	v_add_f32_e32 v80, v86, v80
	v_add_f32_e32 v81, v87, v81
	v_mov_b32_e32 v86, v76
	v_mov_b32_e32 v87, v82
	v_add_f32_e32 v80, v80, v86
	v_add_f32_e32 v81, v81, v87
	v_mov_b32_e32 v82, v77
	v_add_f32_e32 v76, v80, v82
	v_add_f32_e32 v77, v81, v83
	s_nop 1
	v_mov_b32_dpp v81, v77 quad_perm:[1,0,3,2] row_mask:0xf bank_mask:0xf
	v_mov_b32_dpp v80, v76 quad_perm:[1,0,3,2] row_mask:0xf bank_mask:0xf
	v_rsq_f32_e32 v33, v33
	v_mov_b32_e32 v49, v32
	v_mov_b32_e32 v53, v36
	v_mov_b32_e32 v57, v40
	s_waitcnt lgkmcnt(0)
	v_add_f32_e32 v76, v76, v80
	v_add_f32_e32 v77, v77, v81
	s_nop 1
	v_mov_b32_dpp v81, v77 quad_perm:[2,3,0,1] row_mask:0xf bank_mask:0xf
	v_mov_b32_dpp v80, v76 quad_perm:[2,3,0,1] row_mask:0xf bank_mask:0xf
	v_mul_f32_e32 v37, 0x45800000, v33
	v_cndmask_b32_e32 v33, v33, v37, vcc
	v_mul_f32_e32 v37, v33, v143
	v_mul_f32_e32 v41, v5, v37
	s_waitcnt lgkmcnt(0)
	v_add_f32_e32 v76, v76, v80
	v_add_f32_e32 v77, v77, v81
	s_nop 1
	v_mov_b32_dpp v81, v77 row_half_mirror row_mask:0xf bank_mask:0xf
	v_mov_b32_dpp v80, v76 row_half_mirror row_mask:0xf bank_mask:0xf
	v_mul_f32_e32 v5, v33, v141
	v_mul_f32_e32 v45, v13, v5
	v_mul_f32_e32 v5, v33, v125
	v_mul_f32_e32 v5, v17, v5
	s_waitcnt lgkmcnt(0)
	v_add_f32_e32 v76, v76, v80
	v_add_f32_e32 v77, v77, v81
	s_nop 1
	v_mov_b32_dpp v81, v77 row_mirror row_mask:0xf bank_mask:0xf
	v_mov_b32_dpp v80, v76 row_mirror row_mask:0xf bank_mask:0xf
	v_mul_f32_e32 v13, v33, v121
	v_mul_f32_e32 v17, v33, v142
	v_mul_f32_e32 v13, v21, v13
	v_mul_f32_e32 v21, v1, v17
	v_mul_f32_e32 v1, v33, v140
	s_waitcnt lgkmcnt(0)
	v_add_f32_e32 v76, v76, v80
	v_add_f32_e32 v77, v77, v81
	v_mul_f32_e32 v109, v9, v1
	v_mul_f32_e32 v1, v33, v124
	v_fma_f32 v76, v76, s46, v78
	v_fma_f32 v77, v77, s46, v78
	v_mul_f32_e32 v17, v25, v1
	v_mul_f32_e32 v9, 0x4b800000, v77
	v_cmp_gt_f32_e32 vcc, s60, v77
	v_mul_f32_e32 v25, 0x4b800000, v76
	v_cmp_gt_f32_e64 s[0:1], s60, v76
	v_cndmask_b32_e32 v9, v77, v9, vcc
	v_mul_f32_e32 v1, v33, v120
	v_cndmask_b32_e64 v25, v76, v25, s[0:1]
	v_mul_f32_e32 v76, v126, v142
	v_mul_f32_e32 v77, v126, v143
	v_mul_f32_e32 v32, v48, v76
	v_mul_f32_e32 v33, v49, v77
	s_waitcnt vmcnt(7)
	v_mov_b32_e32 v76, v85
	s_waitcnt vmcnt(6)
	v_mov_b32_e32 v77, v84
	v_rsq_f32_e32 v9, v9
	v_mul_f32_e32 v48, v32, v84
	v_mul_f32_e32 v49, v33, v85
	v_mul_f32_e32 v32, v32, v76
	v_mul_f32_e32 v33, v33, v77
	v_mul_f32_e32 v76, v126, v140
	v_mul_f32_e32 v77, v126, v141
	v_rsq_f32_e32 v25, v25
	v_mul_f32_e32 v36, v52, v76
	v_mul_f32_e32 v37, v53, v77
	s_waitcnt vmcnt(5)
	v_mov_b32_e32 v76, v97
	s_waitcnt vmcnt(4)
	v_mov_b32_e32 v77, v96
	v_mul_f32_e32 v52, v36, v96
	v_mul_f32_e32 v53, v37, v97
	v_mul_f32_e32 v36, v36, v76
	v_mul_f32_e32 v37, v37, v77
	v_mul_f32_e32 v76, v126, v124
	v_mul_f32_e32 v77, v126, v125
	v_mul_f32_e32 v56, v56, v76
	v_mul_f32_e32 v57, v57, v77
	s_waitcnt vmcnt(3)
	v_mov_b32_e32 v78, v101
	s_waitcnt vmcnt(2)
	v_mov_b32_e32 v79, v100
	v_mul_f32_e32 v110, v29, v1
	v_mul_f32_e32 v1, 0x45800000, v9
	v_mul_f32_e32 v76, v56, v100
	v_mul_f32_e32 v77, v57, v101
	v_mul_f32_e32 v56, v56, v78
	v_mul_f32_e32 v57, v57, v79
	v_mul_f32_e32 v78, v126, v120
	v_mul_f32_e32 v79, v126, v121
	v_mov_b32_e32 v61, v44
	v_cndmask_b32_e32 v148, v9, v1, vcc
	v_mul_f32_e32 v1, 0x45800000, v25
	v_mul_f32_e32 v60, v60, v78
	v_mul_f32_e32 v61, v61, v79
	v_cndmask_b32_e64 v146, v25, v1, s[0:1]
	s_waitcnt vmcnt(0)
	v_mul_f32_e32 v78, v60, v102
	v_mul_f32_e32 v79, v61, v103
	v_mov_b32_e32 v80, v103
	v_mov_b32_e32 v81, v102
	v_cndmask_b32_e64 v64, v202, 1.0, s[56:57]
	v_mul_f32_e32 v60, v60, v80
	v_mul_f32_e32 v61, v61, v81
	v_or_b32_e32 v80, 0x100, v144
	v_mov_b32_e32 v81, v145
	v_lshl_add_u64 v[82:83], s[6:7], 0, v[80:81]
	v_lshl_add_u64 v[80:81], s[8:9], 0, v[80:81]
	s_waitcnt vmcnt(0)
	v_mov_b32_e32 v1, v188
	v_mov_b32_e32 v9, v189
	v_or_b32_e32 v80, 0x140, v144
	v_mov_b32_e32 v81, v145
	v_lshl_add_u64 v[82:83], s[6:7], 0, v[80:81]
	v_lshl_add_u64 v[80:81], s[8:9], 0, v[80:81]
	v_or_b32_e32 v84, 0x180, v144
	v_mov_b32_e32 v85, v145
	v_lshl_add_u64 v[86:87], s[6:7], 0, v[84:85]
	v_lshl_add_u64 v[84:85], s[8:9], 0, v[84:85]
	v_mov_b32_e32 v25, v190
	v_mov_b32_e32 v29, v191
	v_mov_b32_e32 v40, v208
	v_mov_b32_e32 v44, v209
	v_or_b32_e32 v80, 0x1c0, v144
	v_mov_b32_e32 v81, v145
	v_lshl_add_u64 v[82:83], s[6:7], 0, v[80:81]
	v_lshl_add_u64 v[80:81], s[8:9], 0, v[80:81]
	v_mov_b32_e32 v89, v210
	v_mov_b32_e32 v93, v211
	v_mov_b32_e32 v82, v33
	v_mov_b32_e32 v84, v37
	v_mov_b32_e32 v80, v49
	v_mov_b32_e32 v86, v53
	v_mov_b32_e32 v90, v77
	v_mov_b32_e32 v94, v57
	v_mov_b32_e32 v96, v79
	v_mov_b32_e32 v98, v61
	s_waitcnt vmcnt(7)
	v_mul_f32_e32 v33, v204, v1
	s_waitcnt vmcnt(6)
	v_mul_f32_e32 v83, v127, v9
	v_mul_f32_e32 v81, v127, v1
	v_mul_f32_e32 v49, v204, v9
	v_add_f32_e32 v32, v32, v82
	v_add_f32_e32 v33, v33, v83
	v_add_f32_e64 v48, v80, -v48
	v_add_f32_e64 v49, v81, -v49
	s_waitcnt vmcnt(5)
	v_mul_f32_e32 v37, v104, v25
	s_waitcnt vmcnt(4)
	v_mul_f32_e32 v85, v150, v29
	v_mul_f32_e32 v87, v150, v25
	v_mul_f32_e32 v53, v104, v29
	s_waitcnt vmcnt(3)
	v_mul_f32_e32 v91, v151, v40
	s_waitcnt vmcnt(2)
	v_mul_f32_e32 v77, v105, v44
	v_mul_f32_e32 v95, v151, v44
	v_mul_f32_e32 v57, v105, v40
	s_waitcnt vmcnt(1)
	v_mul_f32_e32 v97, v203, v89
	s_waitcnt vmcnt(0)
	v_mul_f32_e32 v79, v106, v93
	v_mul_f32_e32 v99, v203, v93
	v_mul_f32_e32 v61, v106, v89
	v_add_f32_e32 v36, v36, v84
	v_add_f32_e32 v37, v37, v85
	v_add_f32_e32 v56, v56, v94
	v_add_f32_e32 v57, v57, v95
	v_add_f32_e32 v60, v60, v98
	v_add_f32_e32 v61, v61, v99
	v_mul_f32_e32 v84, v64, v32
	v_mul_f32_e32 v85, v64, v33
	v_add_f32_e64 v32, v86, -v52
	v_add_f32_e64 v33, v87, -v53
	v_mul_f32_e32 v86, v64, v36
	v_mul_f32_e32 v87, v64, v37
	v_add_f32_e64 v36, v90, -v76
	v_add_f32_e64 v37, v91, -v77
	v_add_f32_e64 v52, v96, -v78
	v_add_f32_e64 v53, v97, -v79
	v_mul_f32_e32 v90, v64, v56
	v_mul_f32_e32 v91, v64, v57
	v_mul_f32_e32 v76, v64, v48
	v_mul_f32_e32 v77, v64, v49
	v_mul_f32_e32 v78, v64, v32
	v_mul_f32_e32 v79, v64, v33
	v_mul_f32_e32 v80, v64, v36
	v_mul_f32_e32 v81, v64, v37
	v_mul_f32_e32 v82, v64, v52
	v_mul_f32_e32 v83, v64, v53
	v_mul_f32_e32 v94, v64, v60
	v_mul_f32_e32 v95, v64, v61
	v_or_b32_e32 v32, 0x200, v144
	v_mov_b32_e32 v33, v145
	v_or_b32_e32 v48, 0x240, v144
	v_mov_b32_e32 v49, v145
	v_lshl_add_u64 v[36:37], s[6:7], 0, v[32:33]
	v_lshl_add_u64 v[32:33], s[8:9], 0, v[32:33]
	v_lshl_add_u64 v[52:53], s[6:7], 0, v[48:49]
	v_lshl_add_u64 v[48:49], s[8:9], 0, v[48:49]
	v_or_b32_e32 v56, 0x280, v144
	v_mov_b32_e32 v57, v145
	v_lshl_add_u64 v[60:61], s[6:7], 0, v[56:57]
	v_lshl_add_u64 v[56:57], s[8:9], 0, v[56:57]
	s_waitcnt vmcnt(0)
	v_mov_b32_e32 v37, v232
	s_nop 0
	v_mov_b32_e32 v36, v233
	s_nop 0
	v_mov_b32_e32 v33, v234
	v_mov_b32_e32 v32, v235
	s_nop 0
	v_mov_b32_e32 v49, v236
	v_mov_b32_e32 v48, v237
	v_or_b32_e32 v52, 0x2c0, v144
	v_mov_b32_e32 v53, v145
	v_lshl_add_u64 v[56:57], s[6:7], 0, v[52:53]
	v_lshl_add_u64 v[52:53], s[8:9], 0, v[52:53]
	v_mov_b32_e32 v57, v238
	s_nop 0
	v_mov_b32_e32 v56, v239
	v_mul_f32_e32 v52, v92, v142
	v_mul_f32_e32 v53, v92, v143
	v_mov_b32_e32 v60, v50
	v_mov_b32_e32 v61, v34
	v_mul_f32_e32 v96, v92, v140
	v_mul_f32_e32 v97, v92, v141
	v_mov_b32_e32 v98, v54
	v_mov_b32_e32 v99, v38
	v_mul_f32_e32 v100, v92, v124
	v_mul_f32_e32 v101, v92, v125
	v_mov_b32_e32 v102, v58
	v_mov_b32_e32 v103, v42
	v_mul_f32_e32 v93, v92, v121
	v_mul_f32_e32 v92, v92, v120
	v_mov_b32_e32 v104, v62
	v_mov_b32_e32 v105, v46
	v_mul_f32_e32 v52, v60, v52
	v_mul_f32_e32 v53, v61, v53
	v_mul_f32_e32 v60, v98, v96
	v_mul_f32_e32 v61, v99, v97
	v_mul_f32_e32 v96, v102, v100
	v_mul_f32_e32 v97, v103, v101
	v_mul_f32_e32 v92, v104, v92
	v_mul_f32_e32 v93, v105, v93
	s_waitcnt vmcnt(7)
	v_mov_b32_e32 v100, v37
	s_waitcnt vmcnt(6)
	v_mul_f32_e32 v98, v52, v36
	v_mul_f32_e32 v99, v53, v37
	v_mov_b32_e32 v101, v36
	s_waitcnt vmcnt(4)
	v_mul_f32_e32 v102, v60, v32
	v_mul_f32_e32 v103, v61, v33
	v_mov_b32_e32 v36, v33
	v_mov_b32_e32 v37, v32
	s_waitcnt vmcnt(2)
	v_mul_f32_e32 v104, v96, v48
	v_mul_f32_e32 v105, v97, v49
	v_mov_b32_e32 v32, v49
	v_mov_b32_e32 v33, v48
	s_waitcnt vmcnt(1)
	v_mov_b32_e32 v106, v57
	s_waitcnt vmcnt(0)
	v_mov_b32_e32 v107, v56
	v_mul_f32_e32 v106, v92, v106
	v_mul_f32_e32 v107, v93, v107
	v_mul_f32_e32 v48, v92, v56
	v_mul_f32_e32 v49, v93, v57
	v_mul_f32_e32 v52, v52, v100
	v_mul_f32_e32 v53, v53, v101
	v_mul_f32_e32 v56, v60, v36
	v_mul_f32_e32 v57, v61, v37
	v_mul_f32_e32 v60, v96, v32
	v_mul_f32_e32 v61, v97, v33
	v_or_b32_e32 v32, 0x300, v144
	v_mov_b32_e32 v33, v145
	v_or_b32_e32 v92, 0x340, v144
	v_mov_b32_e32 v93, v145
	v_lshl_add_u64 v[36:37], s[6:7], 0, v[32:33]
	v_lshl_add_u64 v[96:97], s[6:7], 0, v[92:93]
	v_lshl_add_u64 v[92:93], s[8:9], 0, v[92:93]
	v_or_b32_e32 v100, 0x380, v144
	v_mov_b32_e32 v101, v145
	v_lshl_add_u64 v[32:33], s[8:9], 0, v[32:33]
	v_lshl_add_u64 v[112:113], s[6:7], 0, v[100:101]
	v_lshl_add_u64 v[100:101], s[8:9], 0, v[100:101]
	s_waitcnt vmcnt(0)
	v_mov_b32_e32 v114, v240
	v_mov_b32_e32 v115, v241
	s_nop 0
	v_mov_b32_e32 v96, v242
	s_nop 0
	v_mov_b32_e32 v97, v243
	s_nop 0
	v_mov_b32_e32 v92, v248
	v_mov_b32_e32 v93, v249
	v_or_b32_e32 v32, 0x3c0, v144
	v_mov_b32_e32 v33, v145
	v_lshl_add_u64 v[36:37], s[6:7], 0, v[32:33]
	v_lshl_add_u64 v[32:33], s[8:9], 0, v[32:33]
	v_mov_b32_e32 v112, v250
	v_mov_b32_e32 v113, v251
	v_mov_b32_e32 v32, v143
	v_mov_b32_e32 v33, v142
	v_mov_b32_e32 v50, v35
	v_mov_b32_e32 v34, v141
	v_mov_b32_e32 v35, v140
	v_mov_b32_e32 v54, v39
	v_mov_b32_e32 v36, v125
	v_mov_b32_e32 v37, v124
	v_mov_b32_e32 v38, v121
	v_mov_b32_e32 v39, v120
	v_mul_f32_e32 v116, v88, v32
	v_mul_f32_e32 v117, v88, v33
	v_mov_b32_e32 v58, v43
	v_mov_b32_e32 v62, v47
	v_mul_f32_e32 v118, v88, v34
	v_mul_f32_e32 v119, v88, v35
	v_mul_f32_e32 v122, v88, v36
	v_mul_f32_e32 v123, v88, v37
	v_mul_f32_e32 v89, v88, v39
	v_mul_f32_e32 v88, v88, v38
	v_mul_f32_e32 v50, v50, v116
	v_mul_f32_e32 v51, v51, v117
	v_mul_f32_e32 v54, v54, v118
	v_mul_f32_e32 v55, v55, v119
	v_mul_f32_e32 v58, v58, v122
	v_mul_f32_e32 v59, v59, v123
	v_mul_f32_e32 v62, v62, v88
	v_mul_f32_e32 v63, v63, v89
	v_mov_b32_e32 v42, v52
	v_mov_b32_e32 v100, v60
	v_mov_b32_e32 v46, v56
	s_waitcnt vmcnt(7)
	v_mov_b32_e32 v117, v114
	s_waitcnt vmcnt(6)
	v_mov_b32_e32 v116, v115
	v_mul_f32_e32 v88, v50, v114
	v_mul_f32_e32 v89, v51, v115
	v_mul_f32_e32 v50, v50, v116
	v_mul_f32_e32 v51, v51, v117
	s_waitcnt vmcnt(3)
	v_mov_b32_e32 v123, v92
	s_waitcnt vmcnt(2)
	v_mov_b32_e32 v122, v93
	v_mul_f32_e32 v114, v54, v96
	v_mul_f32_e32 v115, v55, v97
	v_mov_b32_e32 v118, v97
	v_mov_b32_e32 v119, v96
	v_mul_f32_e32 v96, v58, v92
	v_mul_f32_e32 v97, v59, v93
	v_mul_f32_e32 v58, v58, v122
	v_mul_f32_e32 v59, v59, v123
	v_mov_b32_e32 v43, v51
	v_pk_mov_b32 v[50:51], v[52:53], v[50:51] op_sel:[1,0]
	v_mul_f32_e32 v54, v54, v118
	v_mul_f32_e32 v55, v55, v119
	v_mov_b32_e32 v101, v59
	v_pk_mov_b32 v[58:59], v[60:61], v[58:59] op_sel:[1,0]
	v_add_f32_e32 v42, v42, v50
	v_add_f32_e32 v43, v43, v51
	v_mov_b32_e32 v47, v55
	v_pk_mov_b32 v[54:55], v[56:57], v[54:55] op_sel:[1,0]
	v_add_f32_e32 v50, v100, v58
	v_add_f32_e32 v51, v101, v59
	v_mul_f32_e32 v100, v64, v42
	v_mul_f32_e32 v101, v64, v43
	s_waitcnt vmcnt(0)
	v_mov_b32_e32 v42, v113
	v_mov_b32_e32 v43, v112
	v_mul_f32_e32 v92, v62, v112
	v_mul_f32_e32 v93, v63, v113
	v_pk_mov_b32 v[126:127], v[98:99], v[88:89] op_sel:[1,0]
	v_mov_b32_e32 v99, v89
	v_pk_mov_b32 v[88:89], v[102:103], v[114:115] op_sel:[1,0]
	v_mov_b32_e32 v103, v115
	v_add_f32_e32 v46, v46, v54
	v_add_f32_e32 v47, v47, v55
	v_mul_f32_e32 v42, v62, v42
	v_mul_f32_e32 v43, v63, v43
	v_pk_mov_b32 v[114:115], v[104:105], v[96:97] op_sel:[1,0]
	v_mov_b32_e32 v105, v97
	v_pk_mov_b32 v[96:97], v[48:49], v[92:93] op_sel:[1,0]
	v_mov_b32_e32 v49, v93
	v_add_f32_e64 v52, v88, -v102
	v_add_f32_e64 v53, v89, -v103
	v_mul_f32_e32 v102, v64, v46
	v_mul_f32_e32 v103, v64, v47
	v_mov_b32_e32 v46, v106
	v_mov_b32_e32 v47, v43
	v_pk_mov_b32 v[42:43], v[106:107], v[42:43] op_sel:[1,0]
	v_add_f32_e64 v92, v126, -v98
	v_add_f32_e64 v93, v127, -v99
	v_add_f32_e64 v56, v114, -v104
	v_add_f32_e64 v57, v115, -v105
	v_add_f32_e64 v48, v96, -v48
	v_add_f32_e64 v49, v97, -v49
	v_add_f32_e32 v42, v46, v42
	v_add_f32_e32 v43, v47, v43
	v_mul_f32_e32 v88, v64, v92
	v_mul_f32_e32 v89, v64, v93
	v_mul_f32_e32 v92, v64, v52
	v_mul_f32_e32 v93, v64, v53
	v_mul_f32_e32 v96, v64, v56
	v_mul_f32_e32 v97, v64, v57
	v_mul_f32_e32 v104, v64, v50
	v_mul_f32_e32 v105, v64, v51
	v_mul_f32_e32 v98, v64, v48
	v_mul_f32_e32 v99, v64, v49
	v_mul_f32_e32 v106, v64, v42
	v_mul_f32_e32 v107, v64, v43
	v_or_b32_e32 v42, 0x1000, v144
	v_mov_b32_e32 v43, v145
	v_or_b32_e32 v48, 0x1040, v144
	v_mov_b32_e32 v49, v145
	v_lshl_add_u64 v[46:47], s[6:7], 0, v[42:43]
	v_lshl_add_u64 v[42:43], s[8:9], 0, v[42:43]
	v_lshl_add_u64 v[50:51], s[6:7], 0, v[48:49]
	v_lshl_add_u64 v[48:49], s[8:9], 0, v[48:49]
	v_or_b32_e32 v52, 0x1080, v144
	v_mov_b32_e32 v53, v145
	v_lshl_add_u64 v[54:55], s[6:7], 0, v[52:53]
	v_lshl_add_u64 v[52:53], s[8:9], 0, v[52:53]
	s_waitcnt vmcnt(0)
	v_mov_b32_e32 v47, v252
	s_nop 0
	v_mov_b32_e32 v46, v253
	s_nop 0
	v_mov_b32_e32 v43, v254
	v_mov_b32_e32 v42, v255
	s_nop 0
	v_mov_b32_e32 v49, v66
	v_mov_b32_e32 v48, v67
	v_or_b32_e32 v50, 0x10c0, v144
	v_mov_b32_e32 v51, v145
	v_lshl_add_u64 v[52:53], s[6:7], 0, v[50:51]
	v_lshl_add_u64 v[50:51], s[8:9], 0, v[50:51]
	v_mov_b32_e32 v53, v68
	s_nop 0
	v_mov_b32_e32 v52, v69
	v_mul_f32_e32 v50, v108, v142
	v_mul_f32_e32 v51, v108, v143
	v_mov_b32_e32 v1, v4
	v_mul_f32_e32 v54, v108, v140
	v_mul_f32_e32 v55, v108, v141
	v_mov_b32_e32 v9, v12
	v_mul_f32_e32 v56, v108, v124
	v_mul_f32_e32 v57, v108, v125
	v_mov_b32_e32 v25, v16
	v_mul_f32_e32 v58, v108, v120
	v_mul_f32_e32 v59, v108, v121
	v_mov_b32_e32 v29, v20
	v_mul_f32_e32 v0, v0, v50
	v_mul_f32_e32 v1, v1, v51
	v_mul_f32_e32 v8, v8, v54
	v_mul_f32_e32 v9, v9, v55
	v_mul_f32_e32 v24, v24, v56
	v_mul_f32_e32 v25, v25, v57
	v_mul_f32_e32 v28, v28, v58
	v_mul_f32_e32 v29, v29, v59
	s_waitcnt vmcnt(7)
	v_mov_b32_e32 v54, v47
	s_waitcnt vmcnt(6)
	v_mov_b32_e32 v55, v46
	s_waitcnt vmcnt(5)
	v_mov_b32_e32 v56, v43
	s_waitcnt vmcnt(4)
	v_mov_b32_e32 v57, v42
	s_waitcnt vmcnt(3)
	v_mov_b32_e32 v58, v49
	s_waitcnt vmcnt(2)
	v_mov_b32_e32 v59, v48
	v_mul_f32_e32 v50, v0, v46
	v_mul_f32_e32 v51, v1, v47
	v_mul_f32_e32 v46, v8, v42
	v_mul_f32_e32 v47, v9, v43
	v_mul_f32_e32 v42, v24, v48
	v_mul_f32_e32 v43, v25, v49
	s_waitcnt vmcnt(1)
	v_mov_b32_e32 v60, v53
	s_waitcnt vmcnt(0)
	v_mov_b32_e32 v61, v52
	v_mul_f32_e32 v48, v28, v52
	v_mul_f32_e32 v49, v29, v53
	v_mul_f32_e32 v0, v0, v54
	v_mul_f32_e32 v1, v1, v55
	v_mul_f32_e32 v8, v8, v56
	v_mul_f32_e32 v9, v9, v57
	v_mul_f32_e32 v24, v24, v58
	v_mul_f32_e32 v25, v25, v59
	v_mul_f32_e32 v28, v28, v60
	v_mul_f32_e32 v29, v29, v61
	v_or_b32_e32 v52, 0x1100, v144
	v_mov_b32_e32 v53, v145
	v_lshl_add_u64 v[54:55], s[6:7], 0, v[52:53]
	v_lshl_add_u64 v[52:53], s[8:9], 0, v[52:53]
	s_waitcnt vmcnt(0)
	v_mov_b32_e32 v60, v71
	v_mov_b32_e32 v61, v74
	v_or_b32_e32 v52, 0x1140, v144
	v_mov_b32_e32 v53, v145
	v_or_b32_e32 v56, 0x1180, v144
	v_mov_b32_e32 v57, v145
	v_lshl_add_u64 v[54:55], s[6:7], 0, v[52:53]
	v_lshl_add_u64 v[52:53], s[8:9], 0, v[52:53]
	v_lshl_add_u64 v[58:59], s[6:7], 0, v[56:57]
	v_lshl_add_u64 v[56:57], s[8:9], 0, v[56:57]
	v_mov_b32_e32 v62, v75
	v_mov_b32_e32 v63, v160
	s_nop 0
	v_mov_b32_e32 v58, v161
	s_nop 0
	v_mov_b32_e32 v56, v162
	v_or_b32_e32 v52, 0x11c0, v144
	v_mov_b32_e32 v53, v145
	v_lshl_add_u64 v[54:55], s[6:7], 0, v[52:53]
	v_lshl_add_u64 v[52:53], s[8:9], 0, v[52:53]
	v_mov_b32_e32 v57, v185
	v_mov_b32_e32 v59, v186
	v_mov_b32_e32 v52, v51
	v_mov_b32_e32 v40, v1
	v_mov_b32_e32 v44, v9
	v_mov_b32_e32 v4, v25
	v_mov_b32_e32 v16, v49
	v_mov_b32_e32 v20, v47
	v_mov_b32_e32 v54, v43
	v_mov_b32_e32 v12, v29
	s_waitcnt vmcnt(7)
	v_mul_f32_e32 v53, v41, v60
	s_waitcnt vmcnt(6)
	v_mul_f32_e32 v51, v21, v61
	v_mul_f32_e32 v41, v41, v61
	v_mul_f32_e32 v1, v21, v60
	v_add_f32_e32 v0, v0, v40
	v_add_f32_e32 v1, v1, v41
	s_waitcnt vmcnt(5)
	v_mul_f32_e32 v21, v45, v62
	s_waitcnt vmcnt(4)
	v_mul_f32_e32 v45, v45, v63
	v_mul_f32_e32 v9, v109, v62
	s_waitcnt vmcnt(3)
	v_mul_f32_e32 v55, v5, v58
	s_waitcnt vmcnt(2)
	v_mul_f32_e32 v49, v17, v56
	v_mul_f32_e32 v5, v5, v56
	v_mul_f32_e32 v25, v17, v58
	v_mul_f32_e32 v47, v109, v63
	s_waitcnt vmcnt(0)
	v_mul_f32_e32 v56, v110, v59
	v_mul_f32_e32 v17, v13, v57
	v_mul_f32_e32 v13, v13, v59
	v_mul_f32_e32 v29, v110, v57
	v_add_f32_e32 v8, v8, v44
	v_add_f32_e32 v9, v9, v45
	v_mov_b32_e32 v43, v49
	v_add_f32_e32 v4, v24, v4
	v_add_f32_e32 v5, v25, v5
	v_mov_b32_e32 v49, v56
	v_add_f32_e32 v12, v28, v12
	v_add_f32_e32 v13, v29, v13
	v_add_f32_e64 v24, v52, -v50
	v_add_f32_e64 v25, v53, -v51
	v_mul_f32_e32 v116, v64, v0
	v_mul_f32_e32 v117, v64, v1
	v_add_f32_e64 v0, v20, -v46
	v_add_f32_e64 v1, v21, -v47
	v_mul_f32_e32 v118, v64, v8
	v_mul_f32_e32 v119, v64, v9
	v_add_f32_e64 v8, v54, -v42
	v_add_f32_e64 v9, v55, -v43
	v_mul_f32_e32 v122, v64, v4
	v_mul_f32_e32 v123, v64, v5
	v_add_f32_e64 v4, v16, -v48
	v_add_f32_e64 v5, v17, -v49
	v_mul_f32_e32 v108, v64, v24
	v_mul_f32_e32 v109, v64, v25
	v_mul_f32_e32 v110, v64, v0
	v_mul_f32_e32 v111, v64, v1
	v_mul_f32_e32 v112, v64, v8
	v_mul_f32_e32 v113, v64, v9
	v_mul_f32_e32 v114, v64, v4
	v_mul_f32_e32 v115, v64, v5
	v_mul_f32_e32 v126, v64, v12
	v_mul_f32_e32 v127, v64, v13
	v_or_b32_e32 v0, 0x1200, v144
	v_mov_b32_e32 v1, v145
	v_or_b32_e32 v8, 0x1240, v144
	v_mov_b32_e32 v9, v145
	v_lshl_add_u64 v[4:5], s[6:7], 0, v[0:1]
	v_lshl_add_u64 v[0:1], s[8:9], 0, v[0:1]
	v_lshl_add_u64 v[12:13], s[6:7], 0, v[8:9]
	v_lshl_add_u64 v[8:9], s[8:9], 0, v[8:9]
	v_or_b32_e32 v16, 0x1280, v144
	v_mov_b32_e32 v17, v145
	v_lshl_add_u64 v[20:21], s[6:7], 0, v[16:17]
	v_lshl_add_u64 v[16:17], s[8:9], 0, v[16:17]
	s_waitcnt vmcnt(0)
	v_mov_b32_e32 v5, v187
	s_nop 0
	v_mov_b32_e32 v4, v207
	s_nop 0
	v_mov_b32_e32 v1, v212
	v_mov_b32_e32 v0, v213
	s_nop 0
	v_mov_b32_e32 v9, v214
	v_mov_b32_e32 v8, v216
	v_or_b32_e32 v12, 0x12c0, v144
	v_mov_b32_e32 v13, v145
	v_lshl_add_u64 v[16:17], s[6:7], 0, v[12:13]
	v_lshl_add_u64 v[12:13], s[8:9], 0, v[12:13]
	v_mov_b32_e32 v17, v218
	s_nop 0
	v_mov_b32_e32 v16, v220
	v_mul_f32_e32 v12, v148, v142
	v_mul_f32_e32 v13, v148, v143
	v_mov_b32_e32 v20, v2
	v_mov_b32_e32 v21, v6
	v_mul_f32_e32 v24, v148, v140
	v_mul_f32_e32 v25, v148, v141
	v_mov_b32_e32 v28, v10
	v_mov_b32_e32 v29, v14
	v_mul_f32_e32 v40, v148, v124
	v_mul_f32_e32 v41, v148, v125
	v_mov_b32_e32 v42, v26
	v_mov_b32_e32 v43, v18
	v_mul_f32_e32 v44, v148, v120
	v_mul_f32_e32 v45, v148, v121
	v_mov_b32_e32 v46, v30
	v_mov_b32_e32 v47, v22
	v_mul_f32_e32 v12, v20, v12
	v_mul_f32_e32 v13, v21, v13
	v_mul_f32_e32 v20, v28, v24
	v_mul_f32_e32 v21, v29, v25
	v_mul_f32_e32 v24, v42, v40
	v_mul_f32_e32 v25, v43, v41
	v_mul_f32_e32 v28, v46, v44
	v_mul_f32_e32 v29, v47, v45
	s_waitcnt vmcnt(7)
	v_mov_b32_e32 v42, v5
	s_waitcnt vmcnt(6)
	v_mov_b32_e32 v43, v4
	s_waitcnt vmcnt(5)
	v_mov_b32_e32 v44, v1
	s_waitcnt vmcnt(4)
	v_mov_b32_e32 v45, v0
	s_waitcnt vmcnt(3)
	v_mov_b32_e32 v46, v9
	s_waitcnt vmcnt(2)
	v_mov_b32_e32 v47, v8
	v_mul_f32_e32 v40, v12, v4
	v_mul_f32_e32 v41, v13, v5
	v_mul_f32_e32 v4, v20, v0
	v_mul_f32_e32 v5, v21, v1
	v_mul_f32_e32 v0, v24, v8
	v_mul_f32_e32 v1, v25, v9
	s_waitcnt vmcnt(1)
	v_mov_b32_e32 v48, v17
	s_waitcnt vmcnt(0)
	v_mov_b32_e32 v49, v16
	v_mul_f32_e32 v8, v28, v16
	v_mul_f32_e32 v9, v29, v17
	v_mul_f32_e32 v12, v12, v42
	v_mul_f32_e32 v13, v13, v43
	v_mul_f32_e32 v16, v20, v44
	v_mul_f32_e32 v17, v21, v45
	v_mul_f32_e32 v20, v24, v46
	v_mul_f32_e32 v21, v25, v47
	v_mul_f32_e32 v24, v28, v48
	v_mul_f32_e32 v25, v29, v49
	v_or_b32_e32 v28, 0x1300, v144
	v_mov_b32_e32 v29, v145
	v_or_b32_e32 v44, 0x1340, v144
	v_mov_b32_e32 v45, v145
	v_lshl_add_u64 v[42:43], s[6:7], 0, v[28:29]
	v_lshl_add_u64 v[28:29], s[8:9], 0, v[28:29]
	v_lshl_add_u64 v[46:47], s[6:7], 0, v[44:45]
	v_lshl_add_u64 v[44:45], s[8:9], 0, v[44:45]
	v_or_b32_e32 v48, 0x1380, v144
	v_mov_b32_e32 v49, v145
	v_or_b32_e32 v144, 0x13c0, v144
	v_lshl_add_u64 v[50:51], s[6:7], 0, v[48:49]
	v_lshl_add_u64 v[48:49], s[8:9], 0, v[48:49]
	s_waitcnt vmcnt(0)
	v_mov_b32_e32 v42, v222
	s_nop 0
	v_mov_b32_e32 v43, v224
	s_nop 0
	v_mov_b32_e32 v28, v226
	v_mov_b32_e32 v29, v228
	s_nop 0
	v_mov_b32_e32 v44, v230
	v_mov_b32_e32 v45, v231
	v_lshl_add_u64 v[46:47], s[6:7], 0, v[144:145]
	v_lshl_add_u64 v[48:49], s[8:9], 0, v[144:145]
	v_mov_b32_e32 v46, v244
	s_nop 0
	v_mov_b32_e32 v47, v245
	v_mul_f32_e32 v32, v32, v146
	v_mul_f32_e32 v33, v33, v146
	v_mov_b32_e32 v2, v7
	v_mul_f32_e32 v34, v34, v146
	v_mul_f32_e32 v35, v35, v146
	v_mov_b32_e32 v10, v15
	v_mul_f32_e32 v36, v36, v146
	v_mul_f32_e32 v37, v37, v146
	v_mov_b32_e32 v26, v19
	v_mul_f32_e32 v38, v38, v146
	v_mul_f32_e32 v39, v39, v146
	v_mov_b32_e32 v30, v23
	v_mul_f32_e32 v2, v2, v32
	v_mul_f32_e32 v3, v3, v33
	v_mul_f32_e32 v10, v10, v34
	v_mul_f32_e32 v11, v11, v35
	v_mul_f32_e32 v26, v26, v36
	v_mul_f32_e32 v27, v27, v37
	v_mul_f32_e32 v30, v30, v38
	v_mul_f32_e32 v31, v31, v39
	v_mov_b32_e32 v6, v12
	v_mov_b32_e32 v14, v16
	v_mov_b32_e32 v18, v20
	v_mov_b32_e32 v22, v24
	s_waitcnt vmcnt(7)
	v_mov_b32_e32 v35, v42
	s_waitcnt vmcnt(6)
	v_mul_f32_e32 v32, v2, v42
	v_mul_f32_e32 v33, v3, v43
	v_mov_b32_e32 v34, v43
	s_waitcnt vmcnt(4)
	v_mul_f32_e32 v36, v10, v28
	v_mul_f32_e32 v37, v11, v29
	v_mov_b32_e32 v38, v29
	v_mov_b32_e32 v39, v28
	s_waitcnt vmcnt(2)
	v_mul_f32_e32 v28, v26, v44
	v_mul_f32_e32 v29, v27, v45
	v_mov_b32_e32 v42, v45
	v_mov_b32_e32 v43, v44
	s_waitcnt vmcnt(0)
	v_mov_b32_e32 v48, v47
	v_mov_b32_e32 v49, v46
	v_mul_f32_e32 v44, v30, v46
	v_mul_f32_e32 v45, v31, v47
	v_pk_mov_b32 v[46:47], v[40:41], v[32:33] op_sel:[1,0]
	v_mov_b32_e32 v41, v33
	v_mul_f32_e32 v2, v2, v34
	v_mul_f32_e32 v3, v3, v35
	v_pk_mov_b32 v[32:33], v[4:5], v[36:37] op_sel:[1,0]
	v_mov_b32_e32 v5, v37
	v_mul_f32_e32 v10, v10, v38
	v_mul_f32_e32 v11, v11, v39
	v_pk_mov_b32 v[34:35], v[0:1], v[28:29] op_sel:[1,0]
	v_mov_b32_e32 v1, v29
	v_mul_f32_e32 v26, v26, v42
	v_mul_f32_e32 v27, v27, v43
	v_mul_f32_e32 v30, v30, v48
	v_mul_f32_e32 v31, v31, v49
	v_pk_mov_b32 v[28:29], v[8:9], v[44:45] op_sel:[1,0]
	v_mov_b32_e32 v9, v45
	v_mov_b32_e32 v7, v3
	v_pk_mov_b32 v[2:3], v[12:13], v[2:3] op_sel:[1,0]
	v_add_f32_e64 v4, v32, -v4
	v_add_f32_e64 v5, v33, -v5
	v_mov_b32_e32 v15, v11
	v_pk_mov_b32 v[10:11], v[16:17], v[10:11] op_sel:[1,0]
	v_add_f32_e64 v0, v34, -v0
	v_add_f32_e64 v1, v35, -v1
	v_mov_b32_e32 v19, v27
	v_pk_mov_b32 v[12:13], v[20:21], v[26:27] op_sel:[1,0]
	v_mov_b32_e32 v23, v31
	v_pk_mov_b32 v[16:17], v[24:25], v[30:31] op_sel:[1,0]
	v_add_f32_e64 v36, v46, -v40
	v_add_f32_e64 v37, v47, -v41
	v_add_f32_e64 v8, v28, -v8
	v_add_f32_e64 v9, v29, -v9
	v_add_f32_e32 v2, v6, v2
	v_add_f32_e32 v3, v7, v3
	v_mul_f32_e32 v124, v64, v4
	v_mul_f32_e32 v125, v64, v5
	v_add_f32_e32 v4, v14, v10
	v_add_f32_e32 v5, v15, v11
	v_mul_f32_e32 v140, v64, v0
	v_mul_f32_e32 v141, v64, v1
	v_add_f32_e32 v0, v18, v12
	v_add_f32_e32 v1, v19, v13
	v_add_f32_e32 v6, v22, v16
	v_add_f32_e32 v7, v23, v17
	v_mul_f32_e32 v120, v64, v36
	v_mul_f32_e32 v121, v64, v37
	v_mul_f32_e32 v142, v64, v8
	v_mul_f32_e32 v143, v64, v9
	v_mul_f32_e32 v144, v64, v2
	v_mul_f32_e32 v145, v64, v3
	v_mul_f32_e32 v146, v64, v4
	v_mul_f32_e32 v147, v64, v5
	v_mul_f32_e32 v148, v64, v0
	v_mul_f32_e32 v149, v64, v1
	v_mul_f32_e32 v150, v64, v6
	v_mul_f32_e32 v151, v64, v7
.Lmy_rp_join:
	s_and_b64 s[0:1], s[56:57], exec
	s_cselect_b32 s0, s61, 0xba00000
	s_add_u32 s4, s50, s0
	s_addc_u32 s5, s51, 0
	s_lshl_b64 s[0:1], s[54:55], 1
	s_add_u32 s0, s4, s0
	s_addc_u32 s1, s5, s1
	s_lshl_b32 s4, s33, 8
	s_add_u32 s56, s0, s4
	s_addc_u32 s57, s1, 0
	s_cbranch_execnz .LBB0_441
